# first K-half of every GEMM unit peeled with srcC = 0; the header no longer zeroes the 64 accumulators
# baseline (speedup 1.0000x reference)
.LBB0_127:
	v_mov_b32_e32 v67, v169
	s_mov_b32 s11, s8
	v_lshrrev_b32_e32 v69, 4, v67
	v_ashrrev_i32_e32 v71, 3, v67
	v_lshrrev_b32_e32 v77, 1, v67
	v_and_b32_e32 v80, 4, v69
	v_and_b32_e32 v81, 3, v71
	v_and_b32_e32 v73, 7, v67
	v_xor_b32_e32 v75, v71, v67
	v_and_b32_e32 v77, 16, v77
	v_and_b32_e32 v79, 8, v69
	v_or_b32_e32 v82, v80, v81
	v_lshlrev_b32_e32 v75, 4, v75
	v_or3_b32 v77, v77, v79, v82
	v_bitop3_b32 v79, v80, v73, v81 bitop3:0x36
	v_lshlrev_b32_e32 v71, 7, v71
	v_lshlrev_b32_e32 v79, 4, v79
	v_and_or_b32 v122, v75, s24, v71
	v_lshl_or_b32 v121, v77, 7, v79
	v_lshlrev_b32_e32 v34, 7, v67
	v_and_b32_e32 v35, 0x780, v34
	v_and_b32_e32 v123, 0x2780, v34
	v_bitop3_b32 v34, v69, v73, 3 bitop3:0x6c
	v_bfe_u32 v77, v67, 4, 2
	v_lshlrev_b32_e32 v124, 4, v34
	v_lshlrev_b32_e32 v34, 6, v67
	v_mov_b32_e32 v75, v1
	v_and_or_b32 v125, v34, s30, v35
	v_bitop3_b32 v34, v77, v73, 4 bitop3:0x36
	v_mov_b32_e32 v73, v1
	v_mov_b32_e32 v67, v1
	v_mov_b32_e32 v69, v1
	v_mov_b32_e32 v77, v1
	v_mov_b32_e32 v71, v1
	v_mov_b32_e32 v79, v1
	v_lshl_add_u64 v[100:101], v[74:75], 1, s[28:29]
	s_mov_b32 s5, s10
	s_mov_b32 s4, s9
	v_lshlrev_b32_e32 v126, 4, v34
	v_lshl_add_u64 v[98:99], v[72:73], 1, s[28:29]
	v_lshl_add_u64 v[102:103], v[76:77], 1, s[28:29]
	v_lshl_add_u64 v[104:105], v[78:79], 1, s[28:29]
	v_lshlrev_b64 v[106:107], 1, v[0:1]
	v_lshlrev_b64 v[108:109], 1, v[66:67]
	v_lshlrev_b64 v[110:111], 1, v[68:69]
	v_lshlrev_b64 v[112:113], 1, v[70:71]
	s_mov_b32 s8, -2
	s_mov_b64 s[42:43], s[72:73]
	s_waitcnt vmcnt(4)
	s_waitcnt lgkmcnt(0)
	s_barrier
	v_add_u32_e32 v127, v124, v123
	v_add_u32_e32 v129, v124, v125
	v_add_u32_e32 v128, v126, v125
	v_add_u32_e32 v130, v126, v123
	v_lshrrev_b32_e32 v218, 6, v169
	v_lshlrev_b32_e32 v218, 10, v218
	v_lshrrev_b32_e32 v219, 3, v169
	v_readfirstlane_b32 s100, v218
	v_and_b32_e32 v218, 3, v219
	v_bfe_u32 v220, v219, 4, 1
	v_lshl_or_b32 v218, v220, 2, v218
	v_bfe_u32 v220, v219, 2, 1
	v_lshl_or_b32 v218, v220, 3, v218
	v_bfe_u32 v220, v219, 3, 1
	v_lshl_or_b32 v218, v220, 4, v218
	v_sub_u32_e32 v218, v218, v219
	v_mul_i32_i24_e32 v218, 0x1600, v218
	v_and_b32_e32 v219, 7, v219
	v_lshlrev_b32_e32 v219, 4, v219
	v_add_u32_e32 v206, 0x7511000, v106
	v_xor_b32_e32 v194, v206, v219
	v_mov_b32_e32 v207, v98
	v_add_u32_e32 v195, v207, v218
	v_xor_b32_e32 v195, v195, v219
	v_add_u32_e32 v208, 0x7511000, v108
	v_xor_b32_e32 v196, v208, v219
	v_mov_b32_e32 v209, v100
	v_add_u32_e32 v197, v209, v218
	v_xor_b32_e32 v197, v197, v219
	v_add_u32_e32 v214, 0x7511000, v110
	v_xor_b32_e32 v202, v214, v219
	v_mov_b32_e32 v215, v102
	v_add_u32_e32 v203, v215, v218
	v_xor_b32_e32 v203, v203, v219
	v_add_u32_e32 v216, 0x7511000, v112
	v_xor_b32_e32 v204, v216, v219
	v_mov_b32_e32 v217, v104
	v_add_u32_e32 v205, v217, v218
	v_xor_b32_e32 v205, v205, v219
	s_setprio 1
	s_add_u32 s98, s42, s27
	s_addc_u32 s99, s43, 0
	s_add_u32 s98, s98, 0x80
	s_addc_u32 s99, s99, 0
	ds_read_b128 v[132:135], v127 offset:16384
	ds_read_b128 v[140:143], v129
	ds_read_b128 v[152:155], v127 offset:18432
	ds_read_b128 v[160:163], v127 offset:20480
	ds_read_b128 v[164:167], v127 offset:22528
	ds_read_b128 v[144:147], v129 offset:2048
	ds_read_b128 v[148:151], v129 offset:4096
	ds_read_b128 v[156:159], v129 offset:6144
	s_add_u32 m0, s100, 0x8000
	s_waitcnt lgkmcnt(6)
	v_mfma_f32_16x16x32_bf16 v[34:37], v[132:135], v[140:143], 0
	global_load_lds_dwordx4 v194, s[98:99]
	s_waitcnt lgkmcnt(5)
	v_mfma_f32_16x16x32_bf16 v[94:97], v[152:155], v[140:143], 0
	ds_read_b128 v[198:201], v128
	s_add_u32 m0, s100, 0xc000
	s_waitcnt lgkmcnt(5)
	v_mfma_f32_16x16x32_bf16 v[38:41], v[160:163], v[140:143], 0
	global_load_lds_dwordx4 v195, s[98:99]
	s_waitcnt lgkmcnt(4)
	v_mfma_f32_16x16x32_bf16 v[90:93], v[164:167], v[140:143], 0
	ds_read_b128 v[140:143], v128 offset:2048
	s_add_u32 m0, s100, 0x9000
	s_waitcnt lgkmcnt(4)
	v_mfma_f32_16x16x32_bf16 v[42:45], v[132:135], v[144:147], 0
	global_load_lds_dwordx4 v196, s[98:99]
	v_mfma_f32_16x16x32_bf16 v[86:89], v[152:155], v[144:147], 0
	ds_read_b128 v[210:213], v128 offset:4096
	s_add_u32 m0, s100, 0xd000
	v_mfma_f32_16x16x32_bf16 v[46:49], v[160:163], v[144:147], 0
	global_load_lds_dwordx4 v197, s[98:99]
	v_mfma_f32_16x16x32_bf16 v[82:85], v[164:167], v[144:147], 0
	ds_read_b128 v[144:147], v128 offset:6144
	s_add_u32 m0, s100, 0xa000
	s_waitcnt lgkmcnt(5)
	v_mfma_f32_16x16x32_bf16 v[50:53], v[132:135], v[148:151], 0
	global_load_lds_dwordx4 v202, s[98:99]
	v_mfma_f32_16x16x32_bf16 v[78:81], v[152:155], v[148:151], 0
	ds_read_b128 v[222:225], v130 offset:16384
	s_add_u32 m0, s100, 0xe000
	v_mfma_f32_16x16x32_bf16 v[54:57], v[160:163], v[148:151], 0
	global_load_lds_dwordx4 v203, s[98:99]
	v_mfma_f32_16x16x32_bf16 v[70:73], v[164:167], v[148:151], 0
	ds_read_b128 v[148:151], v130 offset:18432
	s_add_u32 m0, s100, 0xb000
	s_waitcnt lgkmcnt(6)
	v_mfma_f32_16x16x32_bf16 v[58:61], v[132:135], v[156:159], 0
	global_load_lds_dwordx4 v204, s[98:99]
	v_mfma_f32_16x16x32_bf16 v[66:69], v[152:155], v[156:159], 0
	ds_read_b128 v[152:155], v130 offset:20480
	s_add_u32 m0, s100, 0xf000
	v_mfma_f32_16x16x32_bf16 v[62:65], v[160:163], v[156:159], 0
	global_load_lds_dwordx4 v205, s[98:99]
	v_mfma_f32_16x16x32_bf16 v[74:77], v[164:167], v[156:159], 0
	ds_read_b128 v[156:159], v130 offset:22528
	s_waitcnt lgkmcnt(3)
	v_mfma_f32_16x16x32_bf16 v[34:37], v[222:225], v[198:201], v[34:37]
	s_waitcnt lgkmcnt(2)
	v_mfma_f32_16x16x32_bf16 v[94:97], v[148:151], v[198:201], v[94:97]
	s_waitcnt lgkmcnt(1)
	v_mfma_f32_16x16x32_bf16 v[38:41], v[152:155], v[198:201], v[38:41]
	s_waitcnt lgkmcnt(0)
	v_mfma_f32_16x16x32_bf16 v[90:93], v[156:159], v[198:201], v[90:93]
	v_mfma_f32_16x16x32_bf16 v[42:45], v[222:225], v[140:143], v[42:45]
	v_mfma_f32_16x16x32_bf16 v[86:89], v[148:151], v[140:143], v[86:89]
	v_mfma_f32_16x16x32_bf16 v[46:49], v[152:155], v[140:143], v[46:49]
	v_mfma_f32_16x16x32_bf16 v[82:85], v[156:159], v[140:143], v[82:85]
	v_mfma_f32_16x16x32_bf16 v[50:53], v[222:225], v[210:213], v[50:53]
	v_mfma_f32_16x16x32_bf16 v[78:81], v[148:151], v[210:213], v[78:81]
	v_mfma_f32_16x16x32_bf16 v[54:57], v[152:155], v[210:213], v[54:57]
	v_mfma_f32_16x16x32_bf16 v[70:73], v[156:159], v[210:213], v[70:73]
	v_mfma_f32_16x16x32_bf16 v[58:61], v[222:225], v[144:147], v[58:61]
	v_mfma_f32_16x16x32_bf16 v[66:69], v[148:151], v[144:147], v[66:69]
	v_mfma_f32_16x16x32_bf16 v[62:65], v[152:155], v[144:147], v[62:65]
	v_mfma_f32_16x16x32_bf16 v[74:77], v[156:159], v[144:147], v[74:77]
	s_waitcnt vmcnt(0)
	s_setprio 0
	s_waitcnt lgkmcnt(0)
	s_barrier
	s_branch .Lk3_odd_128

.Lk3_odd_128:
	s_setprio 1
	s_add_u32 s98, s98, 0x80
	s_addc_u32 s99, s99, 0
	ds_read_b128 v[26:29], v127 offset:49152
	ds_read_b128 v[10:13], v129 offset:32768
	ds_read_b128 v[30:33], v127 offset:51200
	ds_read_b128 v[148:151], v127 offset:53248
	ds_read_b128 v[152:155], v127 offset:55296
	ds_read_b128 v[18:21], v129 offset:34816
	ds_read_b128 v[140:143], v129 offset:36864
	ds_read_b128 v[144:147], v129 offset:38912
	s_add_u32 m0, s100, 0x0
	s_waitcnt lgkmcnt(6)
	v_mfma_f32_16x16x32_bf16 v[34:37], v[26:29], v[10:13], v[34:37]
	global_load_lds_dwordx4 v194, s[98:99]
	s_waitcnt lgkmcnt(5)
	v_mfma_f32_16x16x32_bf16 v[94:97], v[30:33], v[10:13], v[94:97]
	ds_read_b128 v[156:159], v128 offset:32768
	s_add_u32 m0, s100, 0x4000
	s_waitcnt lgkmcnt(5)
	v_mfma_f32_16x16x32_bf16 v[38:41], v[148:151], v[10:13], v[38:41]
	global_load_lds_dwordx4 v195, s[98:99]
	s_waitcnt lgkmcnt(4)
	v_mfma_f32_16x16x32_bf16 v[90:93], v[152:155], v[10:13], v[90:93]
	ds_read_b128 v[164:167], v128 offset:34816
	s_add_u32 m0, s100, 0x1000
	s_waitcnt lgkmcnt(4)
	v_mfma_f32_16x16x32_bf16 v[42:45], v[26:29], v[18:21], v[42:45]
	global_load_lds_dwordx4 v196, s[98:99]
	v_mfma_f32_16x16x32_bf16 v[86:89], v[30:33], v[18:21], v[86:89]
	ds_read_b128 v[198:201], v128 offset:36864
	s_add_u32 m0, s100, 0x5000
	v_mfma_f32_16x16x32_bf16 v[46:49], v[148:151], v[18:21], v[46:49]
	global_load_lds_dwordx4 v197, s[98:99]
	v_mfma_f32_16x16x32_bf16 v[82:85], v[152:155], v[18:21], v[82:85]
	ds_read_b128 v[210:213], v128 offset:38912
	s_add_u32 m0, s100, 0x2000
	s_waitcnt lgkmcnt(5)
	v_mfma_f32_16x16x32_bf16 v[50:53], v[26:29], v[140:143], v[50:53]
	global_load_lds_dwordx4 v202, s[98:99]
	v_mfma_f32_16x16x32_bf16 v[78:81], v[30:33], v[140:143], v[78:81]
	ds_read_b128 v[222:225], v130 offset:49152
	s_add_u32 m0, s100, 0x6000
	v_mfma_f32_16x16x32_bf16 v[54:57], v[148:151], v[140:143], v[54:57]
	global_load_lds_dwordx4 v203, s[98:99]
	v_mfma_f32_16x16x32_bf16 v[70:73], v[152:155], v[140:143], v[70:73]
	ds_read_b128 v[140:143], v130 offset:51200
	s_add_u32 m0, s100, 0x3000
	s_waitcnt lgkmcnt(6)
	v_mfma_f32_16x16x32_bf16 v[58:61], v[26:29], v[144:147], v[58:61]
	global_load_lds_dwordx4 v204, s[98:99]
	v_mfma_f32_16x16x32_bf16 v[66:69], v[30:33], v[144:147], v[66:69]
	ds_read_b128 v[230:233], v130 offset:53248
	s_add_u32 m0, s100, 0x7000
	v_mfma_f32_16x16x32_bf16 v[62:65], v[148:151], v[144:147], v[62:65]
	global_load_lds_dwordx4 v205, s[98:99]
	v_mfma_f32_16x16x32_bf16 v[74:77], v[152:155], v[144:147], v[74:77]
	ds_read_b128 v[144:147], v130 offset:55296
	s_waitcnt lgkmcnt(3)
	v_mfma_f32_16x16x32_bf16 v[34:37], v[222:225], v[156:159], v[34:37]
	s_waitcnt lgkmcnt(2)
	v_mfma_f32_16x16x32_bf16 v[94:97], v[140:143], v[156:159], v[94:97]
	s_waitcnt lgkmcnt(1)
	v_mfma_f32_16x16x32_bf16 v[38:41], v[230:233], v[156:159], v[38:41]
	s_waitcnt lgkmcnt(0)
	v_mfma_f32_16x16x32_bf16 v[90:93], v[144:147], v[156:159], v[90:93]
	v_mfma_f32_16x16x32_bf16 v[42:45], v[222:225], v[164:167], v[42:45]
	v_mfma_f32_16x16x32_bf16 v[86:89], v[140:143], v[164:167], v[86:89]
	v_mfma_f32_16x16x32_bf16 v[46:49], v[230:233], v[164:167], v[46:49]
	v_mfma_f32_16x16x32_bf16 v[82:85], v[144:147], v[164:167], v[82:85]
	v_mfma_f32_16x16x32_bf16 v[50:53], v[222:225], v[198:201], v[50:53]
	v_mfma_f32_16x16x32_bf16 v[78:81], v[140:143], v[198:201], v[78:81]
	v_mfma_f32_16x16x32_bf16 v[54:57], v[230:233], v[198:201], v[54:57]
	v_mfma_f32_16x16x32_bf16 v[70:73], v[144:147], v[198:201], v[70:73]
	v_mfma_f32_16x16x32_bf16 v[58:61], v[222:225], v[210:213], v[58:61]
	v_mfma_f32_16x16x32_bf16 v[66:69], v[140:143], v[210:213], v[66:69]
	v_mfma_f32_16x16x32_bf16 v[62:65], v[230:233], v[210:213], v[62:65]
	v_mfma_f32_16x16x32_bf16 v[74:77], v[144:147], v[210:213], v[74:77]
	s_waitcnt vmcnt(0)
	s_setprio 0
	s_add_i32 s8, s8, 2
	s_add_u32 s42, s42, 0x100
	s_addc_u32 s43, s43, 0
	s_cmp_lt_u32 s8, 40
	s_waitcnt lgkmcnt(0)
	s_barrier
	s_cbranch_scc1 .LBB0_128
	v_mov_b32_e32 v2, v194
	v_mov_b32_e32 v3, v195
	v_mov_b32_e32 v4, v196
	v_mov_b32_e32 v5, v197
	v_mov_b32_e32 v6, v202
	v_mov_b32_e32 v7, v203
	v_mov_b32_e32 v8, v204
	v_mov_b32_e32 v9, v205
	s_add_u32 s98, s42, s27
	s_addc_u32 s99, s43, 0
	s_add_u32 s98, s98, 0x80
	s_addc_u32 s99, s99, 0
	s_add_i32 s8, s11, s2
	s_cmpk_lt_u32 s8, 0x100
	s_cselect_b32 s10, s8, s11
	s_lshr_b32 s9, s10, 3
	s_and_b32 s9, s9, 0x1fffff8
	s_add_i32 s9, s9, s21
	s_and_b32 s11, s10, 7
	s_or_b32 s9, s9, s11
	v_mov_b32_e32 v0, v169
	s_lshl_b32 s9, s9, 7
	s_movk_i32 s11, 0xb00
	v_lshrrev_b32_e32 v98, 3, v0
	v_add_u32_e32 v98, s9, v98
	v_lshlrev_b32_e32 v0, 3, v0
	v_mul_lo_u32 v98, v98, s11
	s_lshl_b32 s10, s10, 4
	v_and_or_b32 v0, v0, 56, v98
	v_mov_b32_e32 v98, v169
	s_and_b32 s10, s10, 0x380
	s_cmpk_gt_u32 s8, 0xff
	s_cselect_b32 s101, 1, 0
	v_lshrrev_b32_e32 v99, 3, v98
	v_add_u32_e32 v99, s10, v99
	v_lshlrev_b32_e32 v98, 3, v98
	v_mul_lo_u32 v99, v99, s11
	v_and_or_b32 v164, v98, 56, v99
	v_add_u32_e32 v114, 0x16000, v0
	v_add_u32_e32 v124, 0x2c000, v0
	v_add_u32_e32 v136, 0x42000, v0
	v_add_u32_e32 v174, 0x16000, v164
	v_add_u32_e32 v176, 0x2c000, v164
	v_add_u32_e32 v178, 0x42000, v164
	s_setprio 1
	ds_read_b128 v[98:101], v127 offset:16384
	ds_read_b128 v[102:105], v129
	ds_read_b128 v[110:113], v127 offset:18432
	ds_read_b128 v[144:147], v127 offset:20480
	ds_read_b128 v[148:151], v127 offset:22528
	ds_read_b128 v[106:109], v129 offset:2048
	ds_read_b128 v[132:135], v129 offset:4096
	ds_read_b128 v[140:143], v129 offset:6144
	v_lshrrev_b32_e32 v14, 3, v169
	v_and_b32_e32 v15, 3, v14
	v_bfe_u32 v16, v14, 4, 1
	v_lshl_or_b32 v15, v16, 2, v15
	v_bfe_u32 v16, v14, 2, 1
	v_lshl_or_b32 v15, v16, 3, v15
	v_bfe_u32 v16, v14, 3, 1
	v_lshl_or_b32 v15, v16, 4, v15
	v_sub_u32_e32 v15, v15, v14
	v_mul_i32_i24_e32 v15, 0xb00, v15
	v_and_b32_e32 v14, 7, v14
	v_lshlrev_b32_e32 v14, 3, v14
	v_xor_b32_e32 v0, v0, v14
	v_add_u32_e32 v164, v164, v15
	v_xor_b32_e32 v164, v164, v14
	v_xor_b32_e32 v114, v114, v14
	v_add_u32_e32 v174, v174, v15
	v_xor_b32_e32 v174, v174, v14
	v_xor_b32_e32 v124, v124, v14
	v_add_u32_e32 v176, v176, v15
	v_xor_b32_e32 v176, v176, v14
	v_xor_b32_e32 v136, v136, v14
	v_add_u32_e32 v178, v178, v15
	v_xor_b32_e32 v178, v178, v14
	v_readlane_b32 s14, v254, 33
	v_readlane_b32 s15, v254, 34
	v_mov_b32_e32 v165, v1
	v_mov_b32_e32 v115, v1
	v_mov_b32_e32 v175, v1
	v_mov_b32_e32 v125, v1
	v_mov_b32_e32 v177, v1
	v_mov_b32_e32 v137, v1
	v_mov_b32_e32 v179, v1
	v_lshl_add_u64 v[180:181], v[0:1], 1, s[14:15]
	v_lshl_add_u64 v[186:187], v[164:165], 1, s[38:39]
	v_lshl_add_u64 v[114:115], v[114:115], 1, s[14:15]
	v_lshl_add_u64 v[174:175], v[174:175], 1, s[38:39]
	v_lshl_add_u64 v[188:189], v[124:125], 1, s[14:15]
	v_lshl_add_u64 v[176:177], v[176:177], 1, s[38:39]
	v_lshl_add_u64 v[136:137], v[136:137], 1, s[14:15]
	v_lshl_add_u64 v[178:179], v[178:179], 1, s[38:39]
	s_add_u32 m0, s100, 0x8000
	s_waitcnt lgkmcnt(6)
	v_mfma_f32_16x16x32_bf16 v[152:155], v[98:101], v[102:105], v[34:37]
	global_load_lds_dwordx4 v2, s[98:99]
	s_waitcnt lgkmcnt(5)
	v_mfma_f32_16x16x32_bf16 v[94:97], v[110:113], v[102:105], v[94:97]
	ds_read_b128 v[156:159], v128
	s_add_u32 m0, s100, 0xc000
	s_waitcnt lgkmcnt(5)
	v_mfma_f32_16x16x32_bf16 v[160:163], v[144:147], v[102:105], v[38:41]
	global_load_lds_dwordx4 v3, s[98:99]
	s_waitcnt lgkmcnt(4)
	v_mfma_f32_16x16x32_bf16 v[90:93], v[148:151], v[102:105], v[90:93]
	ds_read_b128 v[102:105], v128 offset:2048
	s_add_u32 m0, s100, 0x9000
	s_waitcnt lgkmcnt(4)
	v_mfma_f32_16x16x32_bf16 v[164:167], v[98:101], v[106:109], v[42:45]
	global_load_lds_dwordx4 v4, s[98:99]
	v_mfma_f32_16x16x32_bf16 v[86:89], v[110:113], v[106:109], v[86:89]
	ds_read_b128 v[194:197], v128 offset:4096
	s_add_u32 m0, s100, 0xd000
	v_mfma_f32_16x16x32_bf16 v[198:201], v[144:147], v[106:109], v[46:49]
	global_load_lds_dwordx4 v5, s[98:99]
	v_mfma_f32_16x16x32_bf16 v[82:85], v[148:151], v[106:109], v[82:85]
	ds_read_b128 v[106:109], v128 offset:6144
	s_add_u32 m0, s100, 0xa000
	s_waitcnt lgkmcnt(5)
	v_mfma_f32_16x16x32_bf16 v[202:205], v[98:101], v[132:135], v[50:53]
	global_load_lds_dwordx4 v6, s[98:99]
	v_mfma_f32_16x16x32_bf16 v[78:81], v[110:113], v[132:135], v[78:81]
	ds_read_b128 v[206:209], v130 offset:16384
	s_add_u32 m0, s100, 0xe000
	v_mfma_f32_16x16x32_bf16 v[210:213], v[144:147], v[132:135], v[54:57]
	global_load_lds_dwordx4 v7, s[98:99]
	v_mfma_f32_16x16x32_bf16 v[70:73], v[148:151], v[132:135], v[70:73]
	ds_read_b128 v[132:135], v130 offset:18432
	s_add_u32 m0, s100, 0xb000
	s_waitcnt lgkmcnt(6)
	v_mfma_f32_16x16x32_bf16 v[98:101], v[98:101], v[140:143], v[58:61]
	global_load_lds_dwordx4 v8, s[98:99]
	v_mfma_f32_16x16x32_bf16 v[66:69], v[110:113], v[140:143], v[66:69]
	ds_read_b128 v[110:113], v130 offset:20480
	s_add_u32 m0, s100, 0xf000
	v_mfma_f32_16x16x32_bf16 v[144:147], v[144:147], v[140:143], v[62:65]
	global_load_lds_dwordx4 v9, s[98:99]
	v_mfma_f32_16x16x32_bf16 v[74:77], v[148:151], v[140:143], v[74:77]
	ds_read_b128 v[140:143], v130 offset:22528
	s_waitcnt lgkmcnt(3)
	v_mfma_f32_16x16x32_bf16 v[148:151], v[206:209], v[156:159], v[152:155]
	s_waitcnt lgkmcnt(2)
	v_mfma_f32_16x16x32_bf16 v[94:97], v[132:135], v[156:159], v[94:97]
	s_waitcnt lgkmcnt(1)
	v_mfma_f32_16x16x32_bf16 v[152:155], v[110:113], v[156:159], v[160:163]
	s_waitcnt lgkmcnt(0)
	v_mfma_f32_16x16x32_bf16 v[90:93], v[140:143], v[156:159], v[90:93]
	v_mfma_f32_16x16x32_bf16 v[156:159], v[206:209], v[102:105], v[164:167]
	v_mfma_f32_16x16x32_bf16 v[86:89], v[132:135], v[102:105], v[86:89]
	v_mfma_f32_16x16x32_bf16 v[160:163], v[110:113], v[102:105], v[198:201]
	v_mfma_f32_16x16x32_bf16 v[82:85], v[140:143], v[102:105], v[82:85]
	v_mfma_f32_16x16x32_bf16 v[102:105], v[206:209], v[194:197], v[202:205]
	v_mfma_f32_16x16x32_bf16 v[78:81], v[132:135], v[194:197], v[78:81]
	v_mfma_f32_16x16x32_bf16 v[164:167], v[110:113], v[194:197], v[210:213]
	v_mfma_f32_16x16x32_bf16 v[70:73], v[140:143], v[194:197], v[70:73]
	v_mfma_f32_16x16x32_bf16 v[98:101], v[206:209], v[106:109], v[98:101]
	v_mfma_f32_16x16x32_bf16 v[66:69], v[132:135], v[106:109], v[66:69]
	v_mfma_f32_16x16x32_bf16 v[110:113], v[110:113], v[106:109], v[144:147]
	v_mfma_f32_16x16x32_bf16 v[74:77], v[140:143], v[106:109], v[74:77]
	s_waitcnt vmcnt(0)
	s_setprio 0
	s_waitcnt lgkmcnt(0)
	s_barrier
	s_setprio 1
	ds_read_b128 v[26:29], v127 offset:49152
	ds_read_b128 v[10:13], v129 offset:32768
	ds_read_b128 v[30:33], v127 offset:51200
	ds_read_b128 v[132:135], v127 offset:53248
	ds_read_b128 v[140:143], v127 offset:55296
	ds_read_b128 v[18:21], v129 offset:34816
	ds_read_b128 v[106:109], v129 offset:36864
	ds_read_b128 v[122:125], v129 offset:38912
	s_add_u32 m0, s100, 0x0
	s_waitcnt lgkmcnt(6)
	v_mfma_f32_16x16x32_bf16 v[144:147], v[26:29], v[10:13], v[148:151]
	global_load_lds_dwordx4 v[180:181], off
	s_waitcnt lgkmcnt(5)
	v_mfma_f32_16x16x32_bf16 v[94:97], v[30:33], v[10:13], v[94:97]
	ds_read_b128 v[148:151], v128 offset:32768
	s_add_u32 m0, s100, 0x4000
	s_waitcnt lgkmcnt(5)
	v_mfma_f32_16x16x32_bf16 v[152:155], v[132:135], v[10:13], v[152:155]
	global_load_lds_dwordx4 v[186:187], off
	s_waitcnt lgkmcnt(4)
	v_mfma_f32_16x16x32_bf16 v[90:93], v[140:143], v[10:13], v[90:93]
	ds_read_b128 v[194:197], v128 offset:34816
	s_add_u32 m0, s100, 0x1000
	s_waitcnt lgkmcnt(4)
	v_mfma_f32_16x16x32_bf16 v[156:159], v[26:29], v[18:21], v[156:159]
	global_load_lds_dwordx4 v[114:115], off
	v_mfma_f32_16x16x32_bf16 v[86:89], v[30:33], v[18:21], v[86:89]
	ds_read_b128 v[198:201], v128 offset:36864
	s_add_u32 m0, s100, 0x5000
	v_mfma_f32_16x16x32_bf16 v[160:163], v[132:135], v[18:21], v[160:163]
	global_load_lds_dwordx4 v[174:175], off
	v_mfma_f32_16x16x32_bf16 v[82:85], v[140:143], v[18:21], v[82:85]
	ds_read_b128 v[126:129], v128 offset:38912
	s_add_u32 m0, s100, 0x2000
	s_waitcnt lgkmcnt(5)
	v_mfma_f32_16x16x32_bf16 v[202:205], v[26:29], v[106:109], v[102:105]
	global_load_lds_dwordx4 v[188:189], off
	v_mfma_f32_16x16x32_bf16 v[78:81], v[30:33], v[106:109], v[78:81]
	ds_read_b128 v[206:209], v130 offset:49152
	s_add_u32 m0, s100, 0x6000
	v_mfma_f32_16x16x32_bf16 v[164:167], v[132:135], v[106:109], v[164:167]
	global_load_lds_dwordx4 v[176:177], off
	v_mfma_f32_16x16x32_bf16 v[70:73], v[140:143], v[106:109], v[70:73]
	ds_read_b128 v[210:213], v130 offset:51200
	s_add_u32 m0, s100, 0x3000
	s_waitcnt lgkmcnt(6)
	v_mfma_f32_16x16x32_bf16 v[214:217], v[26:29], v[122:125], v[98:101]
	global_load_lds_dwordx4 v[136:137], off
	v_mfma_f32_16x16x32_bf16 v[66:69], v[30:33], v[122:125], v[66:69]
	ds_read_b128 v[218:221], v130 offset:53248
	s_add_u32 m0, s100, 0x7000
	v_mfma_f32_16x16x32_bf16 v[110:113], v[132:135], v[122:125], v[110:113]
	global_load_lds_dwordx4 v[178:179], off
	v_mfma_f32_16x16x32_bf16 v[122:125], v[140:143], v[122:125], v[74:77]
	s_waitcnt lgkmcnt(2)
	v_mfma_f32_16x16x32_bf16 v[132:135], v[206:209], v[148:151], v[144:147]
	s_waitcnt lgkmcnt(0)
	v_mfma_f32_16x16x32_bf16 v[144:147], v[218:221], v[148:151], v[152:155]
	ds_read_b128 v[152:155], v130 offset:55296
	v_mfma_f32_16x16x32_bf16 v[140:143], v[210:213], v[148:151], v[94:97]
	s_waitcnt lgkmcnt(0)
	v_mfma_f32_16x16x32_bf16 v[148:151], v[152:155], v[148:151], v[90:93]
	v_mfma_f32_16x16x32_bf16 v[98:101], v[152:155], v[194:197], v[82:85]
	v_mfma_f32_16x16x32_bf16 v[90:93], v[210:213], v[198:201], v[78:81]
	v_mfma_f32_16x16x32_bf16 v[82:85], v[152:155], v[198:201], v[70:73]
	v_mfma_f32_16x16x32_bf16 v[78:81], v[206:209], v[126:129], v[214:217]
	v_mfma_f32_16x16x32_bf16 v[74:77], v[210:213], v[126:129], v[66:69]
	v_mfma_f32_16x16x32_bf16 v[66:69], v[218:221], v[126:129], v[110:113]
	v_mfma_f32_16x16x32_bf16 v[70:73], v[152:155], v[126:129], v[122:125]
	v_mfma_f32_16x16x32_bf16 v[156:159], v[206:209], v[194:197], v[156:159]
	v_mfma_f32_16x16x32_bf16 v[106:109], v[210:213], v[194:197], v[86:89]
	v_mfma_f32_16x16x32_bf16 v[102:105], v[218:221], v[194:197], v[160:163]
	v_mfma_f32_16x16x32_bf16 v[94:97], v[206:209], v[198:201], v[202:205]
	v_mfma_f32_16x16x32_bf16 v[86:89], v[218:221], v[198:201], v[164:167]
	s_setprio 0
	v_add_u32_e32 v110, s4, v116
	v_ashrrev_i32_e32 v111, 31, v110
	v_readlane_b32 s44, v253, 18
	v_lshlrev_b64 v[112:113], 12, v[110:111]
	v_or_b32_e32 v0, s5, v117
	v_readlane_b32 s58, v253, 32
	v_readlane_b32 s59, v253, 33
	v_lshlrev_b64 v[114:115], 2, v[0:1]
	v_lshl_add_u64 v[166:167], v[110:111], 3, s[0:1]
	v_lshl_add_u64 v[112:113], s[58:59], 0, v[112:113]
	v_lshl_add_u64 v[164:165], v[112:113], 0, v[114:115]
	s_barrier
	v_readlane_b32 s44, v253, 18
	v_readlane_b32 s45, v253, 19
	v_readlane_b32 s46, v253, 20
	v_readlane_b32 s47, v253, 21
	v_readlane_b32 s48, v253, 22
	v_readlane_b32 s49, v253, 23
	v_readlane_b32 s50, v253, 24
	v_readlane_b32 s51, v253, 25
	v_readlane_b32 s52, v253, 26
	v_readlane_b32 s53, v253, 27
	v_readlane_b32 s54, v253, 28
	v_readlane_b32 s55, v253, 29
	v_readlane_b32 s56, v253, 30
	v_readlane_b32 s57, v253, 31
	v_readlane_b32 s58, v253, 32
	v_readlane_b32 s59, v253, 33
	s_mov_b64 s[42:43], -1
	v_or_b32_e32 v0, s5, v117
	v_lshlrev_b32_e32 v0, 2, v0
	v_add_u32_e32 v110, s4, v116
	v_lshlrev_b32_e32 v50, 3, v110
	v_lshlrev_b32_e32 v110, 12, v110
	v_add_u32_e32 v110, v110, v0
	v_add_u32_e32 v111, s4, v118
	v_lshlrev_b32_e32 v54, 3, v111
	v_lshlrev_b32_e32 v111, 12, v111
	v_add_u32_e32 v111, v111, v0
	v_add_u32_e32 v112, s4, v119
	v_lshlrev_b32_e32 v58, 3, v112
	v_lshlrev_b32_e32 v112, 12, v112
	v_add_u32_e32 v112, v112, v0
	v_add_u32_e32 v113, s4, v120
	v_lshlrev_b32_e32 v62, 3, v113
	v_lshlrev_b32_e32 v113, 12, v113
	v_add_u32_e32 v113, v113, v0
	s_mov_b32 s14, 0x3fb504f3
	global_load_dwordx2 v[114:115], v50, s[0:1]
	global_load_dwordx2 v[122:123], v54, s[0:1]
	global_load_dwordx2 v[124:125], v58, s[0:1]
	global_load_dwordx2 v[126:127], v62, s[0:1]
	global_load_dwordx4 v[128:131], v0, s[34:35]
	global_load_dwordx4 v[226:229], v0, s[40:41]
	global_load_dwordx4 v[2:5], v110, s[58:59]
	global_load_dwordx4 v[6:9], v111, s[58:59]
	global_load_dwordx4 v[10:13], v112, s[58:59]
	global_load_dwordx4 v[14:17], v113, s[58:59]
	global_load_dwordx4 v[152:155], v0, s[34:35] offset:16
	global_load_dwordx4 v[230:233], v0, s[40:41] offset:16
	global_load_dwordx4 v[18:21], v110, s[58:59] offset:16
	global_load_dwordx4 v[22:25], v111, s[58:59] offset:16
	global_load_dwordx4 v[26:29], v112, s[58:59] offset:16
	global_load_dwordx4 v[30:33], v113, s[58:59] offset:16
	global_load_dwordx4 v[160:163], v0, s[34:35] offset:128
	global_load_dwordx4 v[234:237], v0, s[40:41] offset:128
	global_load_dwordx4 v[34:37], v110, s[58:59] offset:128
	global_load_dwordx4 v[38:41], v111, s[58:59] offset:128
	global_load_dwordx4 v[42:45], v112, s[58:59] offset:128
	global_load_dwordx4 v[46:49], v113, s[58:59] offset:128
	global_load_dwordx4 v[222:225], v0, s[34:35] offset:144
	global_load_dwordx4 v[238:241], v0, s[40:41] offset:144
	global_load_dwordx4 v[50:53], v110, s[58:59] offset:144
	global_load_dwordx4 v[54:57], v111, s[58:59] offset:144
	global_load_dwordx4 v[58:61], v112, s[58:59] offset:144
	global_load_dwordx4 v[62:65], v113, s[58:59] offset:144
	s_waitcnt vmcnt(21)
	v_pk_add_f32 v[2:3], v[2:3], v[114:115] op_sel_hi:[1,0] neg_lo:[0,1] neg_hi:[0,1]
	v_pk_add_f32 v[4:5], v[4:5], v[114:115] op_sel_hi:[1,0] neg_lo:[0,1] neg_hi:[0,1]
	v_pk_mul_f32 v[2:3], v[2:3], v[114:115] op_sel:[0,1]
	v_pk_mul_f32 v[4:5], v[4:5], v[114:115] op_sel:[0,1]
	v_pk_fma_f32 v[2:3], v[2:3], v[128:129], v[226:227]
	v_pk_fma_f32 v[4:5], v[4:5], v[130:131], v[228:229]
	v_pk_fma_f32 v[132:133], v[2:3], s[14:15], v[132:133] op_sel_hi:[1,0,1]
	v_pk_fma_f32 v[134:135], v[4:5], s[14:15], v[134:135] op_sel_hi:[1,0,1]
	global_store_dwordx4 v110, v[132:135], s[58:59]
	s_waitcnt vmcnt(21)
	v_pk_add_f32 v[6:7], v[6:7], v[122:123] op_sel_hi:[1,0] neg_lo:[0,1] neg_hi:[0,1]
	v_pk_add_f32 v[8:9], v[8:9], v[122:123] op_sel_hi:[1,0] neg_lo:[0,1] neg_hi:[0,1]
	v_pk_mul_f32 v[6:7], v[6:7], v[122:123] op_sel:[0,1]
	v_pk_mul_f32 v[8:9], v[8:9], v[122:123] op_sel:[0,1]
	v_pk_fma_f32 v[6:7], v[6:7], v[128:129], v[226:227]
	v_pk_fma_f32 v[8:9], v[8:9], v[130:131], v[228:229]
	v_pk_fma_f32 v[156:157], v[6:7], s[14:15], v[156:157] op_sel_hi:[1,0,1]
	v_pk_fma_f32 v[158:159], v[8:9], s[14:15], v[158:159] op_sel_hi:[1,0,1]
	global_store_dwordx4 v111, v[156:159], s[58:59]
	s_waitcnt vmcnt(21)
	v_pk_add_f32 v[10:11], v[10:11], v[124:125] op_sel_hi:[1,0] neg_lo:[0,1] neg_hi:[0,1]
	v_pk_add_f32 v[12:13], v[12:13], v[124:125] op_sel_hi:[1,0] neg_lo:[0,1] neg_hi:[0,1]
	v_pk_mul_f32 v[10:11], v[10:11], v[124:125] op_sel:[0,1]
	v_pk_mul_f32 v[12:13], v[12:13], v[124:125] op_sel:[0,1]
	v_pk_fma_f32 v[10:11], v[10:11], v[128:129], v[226:227]
	v_pk_fma_f32 v[12:13], v[12:13], v[130:131], v[228:229]
	v_pk_fma_f32 v[94:95], v[10:11], s[14:15], v[94:95] op_sel_hi:[1,0,1]
	v_pk_fma_f32 v[96:97], v[12:13], s[14:15], v[96:97] op_sel_hi:[1,0,1]
	global_store_dwordx4 v112, v[94:97], s[58:59]
	s_waitcnt vmcnt(21)
	v_pk_add_f32 v[14:15], v[14:15], v[126:127] op_sel_hi:[1,0] neg_lo:[0,1] neg_hi:[0,1]
	v_pk_add_f32 v[16:17], v[16:17], v[126:127] op_sel_hi:[1,0] neg_lo:[0,1] neg_hi:[0,1]
	v_pk_mul_f32 v[14:15], v[14:15], v[126:127] op_sel:[0,1]
	v_pk_mul_f32 v[16:17], v[16:17], v[126:127] op_sel:[0,1]
	v_pk_fma_f32 v[14:15], v[14:15], v[128:129], v[226:227]
	v_pk_fma_f32 v[16:17], v[16:17], v[130:131], v[228:229]
	v_pk_fma_f32 v[78:79], v[14:15], s[14:15], v[78:79] op_sel_hi:[1,0,1]
	v_pk_fma_f32 v[80:81], v[16:17], s[14:15], v[80:81] op_sel_hi:[1,0,1]
	global_store_dwordx4 v113, v[78:81], s[58:59]
	s_waitcnt vmcnt(19)
	v_pk_add_f32 v[18:19], v[18:19], v[114:115] op_sel_hi:[1,0] neg_lo:[0,1] neg_hi:[0,1]
	v_pk_add_f32 v[20:21], v[20:21], v[114:115] op_sel_hi:[1,0] neg_lo:[0,1] neg_hi:[0,1]
	v_pk_mul_f32 v[18:19], v[18:19], v[114:115] op_sel:[0,1]
	v_pk_mul_f32 v[20:21], v[20:21], v[114:115] op_sel:[0,1]
	v_pk_fma_f32 v[18:19], v[18:19], v[152:153], v[230:231]
	v_pk_fma_f32 v[20:21], v[20:21], v[154:155], v[232:233]
	v_pk_fma_f32 v[140:141], v[18:19], s[14:15], v[140:141] op_sel_hi:[1,0,1]
	v_pk_fma_f32 v[142:143], v[20:21], s[14:15], v[142:143] op_sel_hi:[1,0,1]
	global_store_dwordx4 v110, v[140:143], s[58:59] offset:16
	s_waitcnt vmcnt(19)
	v_pk_add_f32 v[22:23], v[22:23], v[122:123] op_sel_hi:[1,0] neg_lo:[0,1] neg_hi:[0,1]
	v_pk_add_f32 v[24:25], v[24:25], v[122:123] op_sel_hi:[1,0] neg_lo:[0,1] neg_hi:[0,1]
	v_pk_mul_f32 v[22:23], v[22:23], v[122:123] op_sel:[0,1]
	v_pk_mul_f32 v[24:25], v[24:25], v[122:123] op_sel:[0,1]
	v_pk_fma_f32 v[22:23], v[22:23], v[152:153], v[230:231]
	v_pk_fma_f32 v[24:25], v[24:25], v[154:155], v[232:233]
	v_pk_fma_f32 v[106:107], v[22:23], s[14:15], v[106:107] op_sel_hi:[1,0,1]
	v_pk_fma_f32 v[108:109], v[24:25], s[14:15], v[108:109] op_sel_hi:[1,0,1]
	global_store_dwordx4 v111, v[106:109], s[58:59] offset:16
	s_waitcnt vmcnt(19)
	v_pk_add_f32 v[26:27], v[26:27], v[124:125] op_sel_hi:[1,0] neg_lo:[0,1] neg_hi:[0,1]
	v_pk_add_f32 v[28:29], v[28:29], v[124:125] op_sel_hi:[1,0] neg_lo:[0,1] neg_hi:[0,1]
	v_pk_mul_f32 v[26:27], v[26:27], v[124:125] op_sel:[0,1]
	v_pk_mul_f32 v[28:29], v[28:29], v[124:125] op_sel:[0,1]
	v_pk_fma_f32 v[26:27], v[26:27], v[152:153], v[230:231]
	v_pk_fma_f32 v[28:29], v[28:29], v[154:155], v[232:233]
	v_pk_fma_f32 v[90:91], v[26:27], s[14:15], v[90:91] op_sel_hi:[1,0,1]
	v_pk_fma_f32 v[92:93], v[28:29], s[14:15], v[92:93] op_sel_hi:[1,0,1]
	global_store_dwordx4 v112, v[90:93], s[58:59] offset:16
	s_waitcnt vmcnt(19)
	v_pk_add_f32 v[30:31], v[30:31], v[126:127] op_sel_hi:[1,0] neg_lo:[0,1] neg_hi:[0,1]
	v_pk_add_f32 v[32:33], v[32:33], v[126:127] op_sel_hi:[1,0] neg_lo:[0,1] neg_hi:[0,1]
	v_pk_mul_f32 v[30:31], v[30:31], v[126:127] op_sel:[0,1]
	v_pk_mul_f32 v[32:33], v[32:33], v[126:127] op_sel:[0,1]
	v_pk_fma_f32 v[30:31], v[30:31], v[152:153], v[230:231]
	v_pk_fma_f32 v[32:33], v[32:33], v[154:155], v[232:233]
	v_pk_fma_f32 v[74:75], v[30:31], s[14:15], v[74:75] op_sel_hi:[1,0,1]
	v_pk_fma_f32 v[76:77], v[32:33], s[14:15], v[76:77] op_sel_hi:[1,0,1]
	global_store_dwordx4 v113, v[74:77], s[58:59] offset:16
	s_waitcnt vmcnt(17)
	v_pk_add_f32 v[34:35], v[34:35], v[114:115] op_sel_hi:[1,0] neg_lo:[0,1] neg_hi:[0,1]
	v_pk_add_f32 v[36:37], v[36:37], v[114:115] op_sel_hi:[1,0] neg_lo:[0,1] neg_hi:[0,1]
	v_pk_mul_f32 v[34:35], v[34:35], v[114:115] op_sel:[0,1]
	v_pk_mul_f32 v[36:37], v[36:37], v[114:115] op_sel:[0,1]
	v_pk_fma_f32 v[34:35], v[34:35], v[160:161], v[234:235]
	v_pk_fma_f32 v[36:37], v[36:37], v[162:163], v[236:237]
	v_pk_fma_f32 v[144:145], v[34:35], s[14:15], v[144:145] op_sel_hi:[1,0,1]
	v_pk_fma_f32 v[146:147], v[36:37], s[14:15], v[146:147] op_sel_hi:[1,0,1]
	global_store_dwordx4 v110, v[144:147], s[58:59] offset:128
	s_waitcnt vmcnt(17)
	v_pk_add_f32 v[38:39], v[38:39], v[122:123] op_sel_hi:[1,0] neg_lo:[0,1] neg_hi:[0,1]
	v_pk_add_f32 v[40:41], v[40:41], v[122:123] op_sel_hi:[1,0] neg_lo:[0,1] neg_hi:[0,1]
	v_pk_mul_f32 v[38:39], v[38:39], v[122:123] op_sel:[0,1]
	v_pk_mul_f32 v[40:41], v[40:41], v[122:123] op_sel:[0,1]
	v_pk_fma_f32 v[38:39], v[38:39], v[160:161], v[234:235]
	v_pk_fma_f32 v[40:41], v[40:41], v[162:163], v[236:237]
	v_pk_fma_f32 v[102:103], v[38:39], s[14:15], v[102:103] op_sel_hi:[1,0,1]
	v_pk_fma_f32 v[104:105], v[40:41], s[14:15], v[104:105] op_sel_hi:[1,0,1]
	global_store_dwordx4 v111, v[102:105], s[58:59] offset:128
	s_waitcnt vmcnt(17)
	v_pk_add_f32 v[42:43], v[42:43], v[124:125] op_sel_hi:[1,0] neg_lo:[0,1] neg_hi:[0,1]
	v_pk_add_f32 v[44:45], v[44:45], v[124:125] op_sel_hi:[1,0] neg_lo:[0,1] neg_hi:[0,1]
	v_pk_mul_f32 v[42:43], v[42:43], v[124:125] op_sel:[0,1]
	v_pk_mul_f32 v[44:45], v[44:45], v[124:125] op_sel:[0,1]
	v_pk_fma_f32 v[42:43], v[42:43], v[160:161], v[234:235]
	v_pk_fma_f32 v[44:45], v[44:45], v[162:163], v[236:237]
	v_pk_fma_f32 v[86:87], v[42:43], s[14:15], v[86:87] op_sel_hi:[1,0,1]
	v_pk_fma_f32 v[88:89], v[44:45], s[14:15], v[88:89] op_sel_hi:[1,0,1]
	global_store_dwordx4 v112, v[86:89], s[58:59] offset:128
	s_waitcnt vmcnt(17)
	v_pk_add_f32 v[46:47], v[46:47], v[126:127] op_sel_hi:[1,0] neg_lo:[0,1] neg_hi:[0,1]
	v_pk_add_f32 v[48:49], v[48:49], v[126:127] op_sel_hi:[1,0] neg_lo:[0,1] neg_hi:[0,1]
	v_pk_mul_f32 v[46:47], v[46:47], v[126:127] op_sel:[0,1]
	v_pk_mul_f32 v[48:49], v[48:49], v[126:127] op_sel:[0,1]
	v_pk_fma_f32 v[46:47], v[46:47], v[160:161], v[234:235]
	v_pk_fma_f32 v[48:49], v[48:49], v[162:163], v[236:237]
	v_pk_fma_f32 v[66:67], v[46:47], s[14:15], v[66:67] op_sel_hi:[1,0,1]
	v_pk_fma_f32 v[68:69], v[48:49], s[14:15], v[68:69] op_sel_hi:[1,0,1]
	global_store_dwordx4 v113, v[66:69], s[58:59] offset:128
	s_waitcnt vmcnt(15)
	v_pk_add_f32 v[50:51], v[50:51], v[114:115] op_sel_hi:[1,0] neg_lo:[0,1] neg_hi:[0,1]
	v_pk_add_f32 v[52:53], v[52:53], v[114:115] op_sel_hi:[1,0] neg_lo:[0,1] neg_hi:[0,1]
	v_pk_mul_f32 v[50:51], v[50:51], v[114:115] op_sel:[0,1]
	v_pk_mul_f32 v[52:53], v[52:53], v[114:115] op_sel:[0,1]
	v_pk_fma_f32 v[50:51], v[50:51], v[222:223], v[238:239]
	v_pk_fma_f32 v[52:53], v[52:53], v[224:225], v[240:241]
	v_pk_fma_f32 v[148:149], v[50:51], s[14:15], v[148:149] op_sel_hi:[1,0,1]
	v_pk_fma_f32 v[150:151], v[52:53], s[14:15], v[150:151] op_sel_hi:[1,0,1]
	global_store_dwordx4 v110, v[148:151], s[58:59] offset:144
	s_waitcnt vmcnt(15)
	v_pk_add_f32 v[54:55], v[54:55], v[122:123] op_sel_hi:[1,0] neg_lo:[0,1] neg_hi:[0,1]
	v_pk_add_f32 v[56:57], v[56:57], v[122:123] op_sel_hi:[1,0] neg_lo:[0,1] neg_hi:[0,1]
	v_pk_mul_f32 v[54:55], v[54:55], v[122:123] op_sel:[0,1]
	v_pk_mul_f32 v[56:57], v[56:57], v[122:123] op_sel:[0,1]
	v_pk_fma_f32 v[54:55], v[54:55], v[222:223], v[238:239]
	v_pk_fma_f32 v[56:57], v[56:57], v[224:225], v[240:241]
	v_pk_fma_f32 v[98:99], v[54:55], s[14:15], v[98:99] op_sel_hi:[1,0,1]
	v_pk_fma_f32 v[100:101], v[56:57], s[14:15], v[100:101] op_sel_hi:[1,0,1]
	global_store_dwordx4 v111, v[98:101], s[58:59] offset:144
	s_waitcnt vmcnt(15)
	v_pk_add_f32 v[58:59], v[58:59], v[124:125] op_sel_hi:[1,0] neg_lo:[0,1] neg_hi:[0,1]
	v_pk_add_f32 v[60:61], v[60:61], v[124:125] op_sel_hi:[1,0] neg_lo:[0,1] neg_hi:[0,1]
	v_pk_mul_f32 v[58:59], v[58:59], v[124:125] op_sel:[0,1]
	v_pk_mul_f32 v[60:61], v[60:61], v[124:125] op_sel:[0,1]
	v_pk_fma_f32 v[58:59], v[58:59], v[222:223], v[238:239]
	v_pk_fma_f32 v[60:61], v[60:61], v[224:225], v[240:241]
	v_pk_fma_f32 v[82:83], v[58:59], s[14:15], v[82:83] op_sel_hi:[1,0,1]
	v_pk_fma_f32 v[84:85], v[60:61], s[14:15], v[84:85] op_sel_hi:[1,0,1]
	global_store_dwordx4 v112, v[82:85], s[58:59] offset:144
	s_waitcnt vmcnt(15)
	v_pk_add_f32 v[62:63], v[62:63], v[126:127] op_sel_hi:[1,0] neg_lo:[0,1] neg_hi:[0,1]
	v_pk_add_f32 v[64:65], v[64:65], v[126:127] op_sel_hi:[1,0] neg_lo:[0,1] neg_hi:[0,1]
	v_pk_mul_f32 v[62:63], v[62:63], v[126:127] op_sel:[0,1]
	v_pk_mul_f32 v[64:65], v[64:65], v[126:127] op_sel:[0,1]
	v_pk_fma_f32 v[62:63], v[62:63], v[222:223], v[238:239]
	v_pk_fma_f32 v[64:65], v[64:65], v[224:225], v[240:241]
	v_pk_fma_f32 v[70:71], v[62:63], s[14:15], v[70:71] op_sel_hi:[1,0,1]
	v_pk_fma_f32 v[72:73], v[64:65], s[14:15], v[72:73] op_sel_hi:[1,0,1]
	global_store_dwordx4 v113, v[70:73], s[58:59] offset:144
	s_cmp_lg_u32 s101, 0
	s_cbranch_scc1 .LBB0_126
	v_mov_b32_e32 v0, v169
	v_mov_b32_e32 v67, v169
	s_movk_i32 s4, 0xb00
	v_lshrrev_b32_e32 v66, 3, v0
	v_lshrrev_b32_e32 v69, 3, v67
	v_add_u32_e32 v66, s9, v66
	v_add_u32_e32 v69, s10, v69
	v_lshlrev_b32_e32 v0, 3, v0
	v_mul_lo_u32 v66, v66, s4
	v_lshlrev_b32_e32 v67, 3, v67
	v_mul_lo_u32 v69, v69, s4
	v_and_or_b32 v0, v0, 56, v66
	v_and_or_b32 v72, v67, 56, v69
	v_add_u32_e32 v66, 0x16000, v0
	v_add_u32_e32 v68, 0x2c000, v0
	v_add_u32_e32 v70, 0x42000, v0
	v_add_u32_e32 v74, 0x16000, v72
	v_add_u32_e32 v76, 0x2c000, v72
	v_add_u32_e32 v78, 0x42000, v72
	s_mov_b64 s[42:43], 0
	s_branch .LBB0_126

.LBB0_136:
	v_mov_b32_e32 v67, v169
	s_mov_b32 s8, s9
	v_lshrrev_b32_e32 v69, 4, v67
	v_ashrrev_i32_e32 v71, 3, v67
	v_lshrrev_b32_e32 v77, 1, v67
	v_and_b32_e32 v80, 4, v69
	v_and_b32_e32 v81, 3, v71
	v_and_b32_e32 v73, 7, v67
	v_xor_b32_e32 v75, v71, v67
	v_and_b32_e32 v77, 16, v77
	v_and_b32_e32 v79, 8, v69
	v_or_b32_e32 v82, v80, v81
	v_lshlrev_b32_e32 v75, 4, v75
	v_or3_b32 v77, v77, v79, v82
	v_bitop3_b32 v79, v80, v73, v81 bitop3:0x36
	v_lshlrev_b32_e32 v71, 7, v71
	v_lshlrev_b32_e32 v79, 4, v79
	v_and_or_b32 v123, v75, s24, v71
	v_lshl_or_b32 v99, v77, 7, v79
	v_lshlrev_b32_e32 v35, 7, v67
	v_bfe_u32 v34, v67, 4, 2
	v_and_b32_e32 v36, 0x780, v35
	v_and_b32_e32 v124, 0x2780, v35
	v_bitop3_b32 v35, v69, v73, 3 bitop3:0x6c
	v_mov_b32_e32 v75, v1
	v_lshlrev_b32_e32 v125, 4, v35
	v_lshlrev_b32_e32 v35, 6, v67
	v_bitop3_b32 v34, v34, v73, 4 bitop3:0x36
	v_mov_b32_e32 v73, v1
	v_mov_b32_e32 v67, v1
	v_mov_b32_e32 v69, v1
	v_mov_b32_e32 v77, v1
	v_mov_b32_e32 v71, v1
	v_mov_b32_e32 v79, v1
	v_lshl_add_u64 v[102:103], v[74:75], 1, s[0:1]
	s_mov_b32 s5, s10
	v_and_or_b32 v126, v35, s30, v36
	v_lshlrev_b32_e32 v127, 4, v34
	v_lshl_add_u64 v[100:101], v[72:73], 1, s[0:1]
	v_lshl_add_u64 v[104:105], v[76:77], 1, s[0:1]
	v_lshl_add_u64 v[106:107], v[78:79], 1, s[0:1]
	v_lshlrev_b64 v[108:109], 1, v[0:1]
	v_lshlrev_b64 v[110:111], 1, v[66:67]
	v_lshlrev_b64 v[112:113], 1, v[68:69]
	v_lshlrev_b64 v[114:115], 1, v[70:71]
	s_mov_b32 s9, -2
	s_mov_b64 s[46:47], s[28:29]
	s_waitcnt vmcnt(4)
	s_waitcnt lgkmcnt(0)
	s_barrier
	v_add_u32_e32 v128, v125, v124
	v_add_u32_e32 v130, v125, v126
	v_add_u32_e32 v129, v127, v126
	v_add_u32_e32 v131, v127, v124
	v_lshrrev_b32_e32 v218, 6, v169
	v_lshlrev_b32_e32 v218, 10, v218
	v_lshrrev_b32_e32 v219, 3, v169
	v_readfirstlane_b32 s100, v218
	v_and_b32_e32 v218, 3, v219
	v_bfe_u32 v220, v219, 4, 1
	v_lshl_or_b32 v218, v220, 2, v218
	v_bfe_u32 v220, v219, 2, 1
	v_lshl_or_b32 v218, v220, 3, v218
	v_bfe_u32 v220, v219, 3, 1
	v_lshl_or_b32 v218, v220, 4, v218
	v_sub_u32_e32 v218, v218, v219
	v_mul_i32_i24_e32 v218, 0x800, v218
	v_and_b32_e32 v219, 7, v219
	v_lshlrev_b32_e32 v219, 4, v219
	v_add_u32_e32 v206, 0x2b11000, v108
	v_xor_b32_e32 v194, v206, v219
	v_mov_b32_e32 v207, v100
	v_add_u32_e32 v195, v207, v218
	v_xor_b32_e32 v195, v195, v219
	v_add_u32_e32 v208, 0x2b11000, v110
	v_xor_b32_e32 v196, v208, v219
	v_mov_b32_e32 v209, v102
	v_add_u32_e32 v197, v209, v218
	v_xor_b32_e32 v197, v197, v219
	v_add_u32_e32 v214, 0x2b11000, v112
	v_xor_b32_e32 v202, v214, v219
	v_mov_b32_e32 v215, v104
	v_add_u32_e32 v203, v215, v218
	v_xor_b32_e32 v203, v203, v219
	v_add_u32_e32 v216, 0x2b11000, v114
	v_xor_b32_e32 v204, v216, v219
	v_mov_b32_e32 v217, v106
	v_add_u32_e32 v205, v217, v218
	v_xor_b32_e32 v205, v205, v219
	s_setprio 1
	s_add_u32 s98, s46, s16
	s_addc_u32 s99, s47, 0
	s_add_u32 s98, s98, 0x80
	s_addc_u32 s99, s99, 0
	ds_read_b128 v[132:135], v128 offset:16384
	ds_read_b128 v[140:143], v130
	ds_read_b128 v[152:155], v128 offset:18432
	ds_read_b128 v[160:163], v128 offset:20480
	ds_read_b128 v[164:167], v128 offset:22528
	ds_read_b128 v[144:147], v130 offset:2048
	ds_read_b128 v[148:151], v130 offset:4096
	ds_read_b128 v[156:159], v130 offset:6144
	s_add_u32 m0, s100, 0x8000
	s_waitcnt lgkmcnt(6)
	v_mfma_f32_16x16x32_bf16 v[34:37], v[132:135], v[140:143], 0
	global_load_lds_dwordx4 v194, s[98:99]
	s_waitcnt lgkmcnt(5)
	v_mfma_f32_16x16x32_bf16 v[94:97], v[152:155], v[140:143], 0
	ds_read_b128 v[198:201], v129
	s_add_u32 m0, s100, 0xc000
	s_waitcnt lgkmcnt(5)
	v_mfma_f32_16x16x32_bf16 v[38:41], v[160:163], v[140:143], 0
	global_load_lds_dwordx4 v195, s[98:99]
	s_waitcnt lgkmcnt(4)
	v_mfma_f32_16x16x32_bf16 v[90:93], v[164:167], v[140:143], 0
	ds_read_b128 v[140:143], v129 offset:2048
	s_add_u32 m0, s100, 0x9000
	s_waitcnt lgkmcnt(4)
	v_mfma_f32_16x16x32_bf16 v[42:45], v[132:135], v[144:147], 0
	global_load_lds_dwordx4 v196, s[98:99]
	v_mfma_f32_16x16x32_bf16 v[86:89], v[152:155], v[144:147], 0
	ds_read_b128 v[210:213], v129 offset:4096
	s_add_u32 m0, s100, 0xd000
	v_mfma_f32_16x16x32_bf16 v[46:49], v[160:163], v[144:147], 0
	global_load_lds_dwordx4 v197, s[98:99]
	v_mfma_f32_16x16x32_bf16 v[82:85], v[164:167], v[144:147], 0
	ds_read_b128 v[144:147], v129 offset:6144
	s_add_u32 m0, s100, 0xa000
	s_waitcnt lgkmcnt(5)
	v_mfma_f32_16x16x32_bf16 v[50:53], v[132:135], v[148:151], 0
	global_load_lds_dwordx4 v202, s[98:99]
	v_mfma_f32_16x16x32_bf16 v[78:81], v[152:155], v[148:151], 0
	ds_read_b128 v[222:225], v131 offset:16384
	s_add_u32 m0, s100, 0xe000
	v_mfma_f32_16x16x32_bf16 v[54:57], v[160:163], v[148:151], 0
	global_load_lds_dwordx4 v203, s[98:99]
	v_mfma_f32_16x16x32_bf16 v[70:73], v[164:167], v[148:151], 0
	ds_read_b128 v[148:151], v131 offset:18432
	s_add_u32 m0, s100, 0xb000
	s_waitcnt lgkmcnt(6)
	v_mfma_f32_16x16x32_bf16 v[58:61], v[132:135], v[156:159], 0
	global_load_lds_dwordx4 v204, s[98:99]
	v_mfma_f32_16x16x32_bf16 v[66:69], v[152:155], v[156:159], 0
	ds_read_b128 v[152:155], v131 offset:20480
	s_add_u32 m0, s100, 0xf000
	v_mfma_f32_16x16x32_bf16 v[62:65], v[160:163], v[156:159], 0
	global_load_lds_dwordx4 v205, s[98:99]
	v_mfma_f32_16x16x32_bf16 v[74:77], v[164:167], v[156:159], 0
	ds_read_b128 v[156:159], v131 offset:22528
	s_waitcnt lgkmcnt(3)
	v_mfma_f32_16x16x32_bf16 v[34:37], v[222:225], v[198:201], v[34:37]
	s_waitcnt lgkmcnt(2)
	v_mfma_f32_16x16x32_bf16 v[94:97], v[148:151], v[198:201], v[94:97]
	s_waitcnt lgkmcnt(1)
	v_mfma_f32_16x16x32_bf16 v[38:41], v[152:155], v[198:201], v[38:41]
	s_waitcnt lgkmcnt(0)
	v_mfma_f32_16x16x32_bf16 v[90:93], v[156:159], v[198:201], v[90:93]
	v_mfma_f32_16x16x32_bf16 v[42:45], v[222:225], v[140:143], v[42:45]
	v_mfma_f32_16x16x32_bf16 v[86:89], v[148:151], v[140:143], v[86:89]
	v_mfma_f32_16x16x32_bf16 v[46:49], v[152:155], v[140:143], v[46:49]
	v_mfma_f32_16x16x32_bf16 v[82:85], v[156:159], v[140:143], v[82:85]
	v_mfma_f32_16x16x32_bf16 v[50:53], v[222:225], v[210:213], v[50:53]
	v_mfma_f32_16x16x32_bf16 v[78:81], v[148:151], v[210:213], v[78:81]
	v_mfma_f32_16x16x32_bf16 v[54:57], v[152:155], v[210:213], v[54:57]
	v_mfma_f32_16x16x32_bf16 v[70:73], v[156:159], v[210:213], v[70:73]
	v_mfma_f32_16x16x32_bf16 v[58:61], v[222:225], v[144:147], v[58:61]
	v_mfma_f32_16x16x32_bf16 v[66:69], v[148:151], v[144:147], v[66:69]
	v_mfma_f32_16x16x32_bf16 v[62:65], v[152:155], v[144:147], v[62:65]
	v_mfma_f32_16x16x32_bf16 v[74:77], v[156:159], v[144:147], v[74:77]
	s_waitcnt vmcnt(0)
	s_setprio 0
	s_waitcnt lgkmcnt(0)
	s_barrier
	s_branch .Lk3_odd_137

.Lk3_odd_137:
	s_setprio 1
	s_add_u32 s98, s98, 0x80
	s_addc_u32 s99, s99, 0
	ds_read_b128 v[26:29], v128 offset:49152
	ds_read_b128 v[10:13], v130 offset:32768
	ds_read_b128 v[30:33], v128 offset:51200
	ds_read_b128 v[148:151], v128 offset:53248
	ds_read_b128 v[152:155], v128 offset:55296
	ds_read_b128 v[18:21], v130 offset:34816
	ds_read_b128 v[140:143], v130 offset:36864
	ds_read_b128 v[144:147], v130 offset:38912
	s_add_u32 m0, s100, 0x0
	s_waitcnt lgkmcnt(6)
	v_mfma_f32_16x16x32_bf16 v[34:37], v[26:29], v[10:13], v[34:37]
	global_load_lds_dwordx4 v194, s[98:99]
	s_waitcnt lgkmcnt(5)
	v_mfma_f32_16x16x32_bf16 v[94:97], v[30:33], v[10:13], v[94:97]
	ds_read_b128 v[156:159], v129 offset:32768
	s_add_u32 m0, s100, 0x4000
	s_waitcnt lgkmcnt(5)
	v_mfma_f32_16x16x32_bf16 v[38:41], v[148:151], v[10:13], v[38:41]
	global_load_lds_dwordx4 v195, s[98:99]
	s_waitcnt lgkmcnt(4)
	v_mfma_f32_16x16x32_bf16 v[90:93], v[152:155], v[10:13], v[90:93]
	ds_read_b128 v[164:167], v129 offset:34816
	s_add_u32 m0, s100, 0x1000
	s_waitcnt lgkmcnt(4)
	v_mfma_f32_16x16x32_bf16 v[42:45], v[26:29], v[18:21], v[42:45]
	global_load_lds_dwordx4 v196, s[98:99]
	v_mfma_f32_16x16x32_bf16 v[86:89], v[30:33], v[18:21], v[86:89]
	ds_read_b128 v[198:201], v129 offset:36864
	s_add_u32 m0, s100, 0x5000
	v_mfma_f32_16x16x32_bf16 v[46:49], v[148:151], v[18:21], v[46:49]
	global_load_lds_dwordx4 v197, s[98:99]
	v_mfma_f32_16x16x32_bf16 v[82:85], v[152:155], v[18:21], v[82:85]
	ds_read_b128 v[210:213], v129 offset:38912
	s_add_u32 m0, s100, 0x2000
	s_waitcnt lgkmcnt(5)
	v_mfma_f32_16x16x32_bf16 v[50:53], v[26:29], v[140:143], v[50:53]
	global_load_lds_dwordx4 v202, s[98:99]
	v_mfma_f32_16x16x32_bf16 v[78:81], v[30:33], v[140:143], v[78:81]
	ds_read_b128 v[222:225], v131 offset:49152
	s_add_u32 m0, s100, 0x6000
	v_mfma_f32_16x16x32_bf16 v[54:57], v[148:151], v[140:143], v[54:57]
	global_load_lds_dwordx4 v203, s[98:99]
	v_mfma_f32_16x16x32_bf16 v[70:73], v[152:155], v[140:143], v[70:73]
	ds_read_b128 v[140:143], v131 offset:51200
	s_add_u32 m0, s100, 0x3000
	s_waitcnt lgkmcnt(6)
	v_mfma_f32_16x16x32_bf16 v[58:61], v[26:29], v[144:147], v[58:61]
	global_load_lds_dwordx4 v204, s[98:99]
	v_mfma_f32_16x16x32_bf16 v[66:69], v[30:33], v[144:147], v[66:69]
	ds_read_b128 v[230:233], v131 offset:53248
	s_add_u32 m0, s100, 0x7000
	v_mfma_f32_16x16x32_bf16 v[62:65], v[148:151], v[144:147], v[62:65]
	global_load_lds_dwordx4 v205, s[98:99]
	v_mfma_f32_16x16x32_bf16 v[74:77], v[152:155], v[144:147], v[74:77]
	ds_read_b128 v[144:147], v131 offset:55296
	s_waitcnt lgkmcnt(3)
	v_mfma_f32_16x16x32_bf16 v[34:37], v[222:225], v[156:159], v[34:37]
	s_waitcnt lgkmcnt(2)
	v_mfma_f32_16x16x32_bf16 v[94:97], v[140:143], v[156:159], v[94:97]
	s_waitcnt lgkmcnt(1)
	v_mfma_f32_16x16x32_bf16 v[38:41], v[230:233], v[156:159], v[38:41]
	s_waitcnt lgkmcnt(0)
	v_mfma_f32_16x16x32_bf16 v[90:93], v[144:147], v[156:159], v[90:93]
	v_mfma_f32_16x16x32_bf16 v[42:45], v[222:225], v[164:167], v[42:45]
	v_mfma_f32_16x16x32_bf16 v[86:89], v[140:143], v[164:167], v[86:89]
	v_mfma_f32_16x16x32_bf16 v[46:49], v[230:233], v[164:167], v[46:49]
	v_mfma_f32_16x16x32_bf16 v[82:85], v[144:147], v[164:167], v[82:85]
	v_mfma_f32_16x16x32_bf16 v[50:53], v[222:225], v[198:201], v[50:53]
	v_mfma_f32_16x16x32_bf16 v[78:81], v[140:143], v[198:201], v[78:81]
	v_mfma_f32_16x16x32_bf16 v[54:57], v[230:233], v[198:201], v[54:57]
	v_mfma_f32_16x16x32_bf16 v[70:73], v[144:147], v[198:201], v[70:73]
	v_mfma_f32_16x16x32_bf16 v[58:61], v[222:225], v[210:213], v[58:61]
	v_mfma_f32_16x16x32_bf16 v[66:69], v[140:143], v[210:213], v[66:69]
	v_mfma_f32_16x16x32_bf16 v[62:65], v[230:233], v[210:213], v[62:65]
	v_mfma_f32_16x16x32_bf16 v[74:77], v[144:147], v[210:213], v[74:77]
	s_waitcnt vmcnt(0)
	s_setprio 0
	s_add_i32 s9, s9, 2
	s_add_u32 s46, s46, 0x100
	s_addc_u32 s47, s47, 0
	s_cmp_lt_u32 s9, 12
	s_waitcnt lgkmcnt(0)
	s_barrier
	s_cbranch_scc1 .LBB0_137
	v_mov_b32_e32 v2, v194
	v_mov_b32_e32 v3, v195
	v_mov_b32_e32 v4, v196
	v_mov_b32_e32 v5, v197
	v_mov_b32_e32 v6, v202
	v_mov_b32_e32 v7, v203
	v_mov_b32_e32 v8, v204
	v_mov_b32_e32 v9, v205
	s_add_u32 s98, s46, s16
	s_addc_u32 s99, s47, 0
	s_add_u32 s98, s98, 0x80
	s_addc_u32 s99, s99, 0
	s_add_i32 s9, s8, s2
	s_cmpk_lt_u32 s9, 0x580
	s_cselect_b32 s8, s9, s8
	s_mul_hi_u32 s10, s8, 0xba2e8ba3
	s_lshr_b32 s10, s10, 8
	s_mul_i32 s11, s10, 0x160
	v_mov_b32_e32 v0, v169
	s_sub_i32 s11, s8, s11
	s_lshl_b32 s8, s10, 3
	s_add_i32 s8, s8, s21
	s_and_b32 s10, s11, 7
	v_lshlrev_b32_e32 v100, 3, v0
	v_lshlrev_b32_e32 v0, 7, v0
	s_or_b32 s8, s8, s10
	v_and_b32_e32 v0, 0xfffffc00, v0
	v_lshl_add_u32 v0, s8, 17, v0
	v_and_or_b32 v0, v100, 56, v0
	v_mov_b32_e32 v100, v169
	s_lshl_b32 s10, s11, 4
	s_and_b32 s10, s10, 0x1f80
	v_lshrrev_b32_e32 v101, 3, v100
	v_lshlrev_b32_e32 v100, 3, v100
	v_add_u32_e32 v101, s10, v101
	v_and_b32_e32 v100, 56, v100
	v_lshl_or_b32 v160, v101, 10, v100
	s_cmpk_gt_u32 s9, 0x57f
	s_cselect_b32 s101, 1, 0
	v_add_u32_e32 v116, 0x8000, v0
	v_add_u32_e32 v136, 0x10000, v0
	v_add_u32_e32 v174, 0x18000, v0
	v_add_u32_e32 v176, 0x8000, v160
	v_add_u32_e32 v178, 0x10000, v160
	v_add_u32_e32 v180, 0x18000, v160
	s_setprio 1
	ds_read_b128 v[100:103], v128 offset:16384
	ds_read_b128 v[104:107], v130
	ds_read_b128 v[112:115], v128 offset:18432
	ds_read_b128 v[140:143], v128 offset:20480
	ds_read_b128 v[144:147], v128 offset:22528
	ds_read_b128 v[108:111], v130 offset:2048
	ds_read_b128 v[124:127], v130 offset:4096
	ds_read_b128 v[132:135], v130 offset:6144
	v_lshrrev_b32_e32 v14, 3, v169
	v_and_b32_e32 v15, 3, v14
	v_bfe_u32 v16, v14, 4, 1
	v_lshl_or_b32 v15, v16, 2, v15
	v_bfe_u32 v16, v14, 2, 1
	v_lshl_or_b32 v15, v16, 3, v15
	v_bfe_u32 v16, v14, 3, 1
	v_lshl_or_b32 v15, v16, 4, v15
	v_sub_u32_e32 v15, v15, v14
	v_mul_i32_i24_e32 v15, 0x400, v15
	v_and_b32_e32 v14, 7, v14
	v_lshlrev_b32_e32 v14, 3, v14
	v_xor_b32_e32 v0, v0, v14
	v_add_u32_e32 v160, v160, v15
	v_xor_b32_e32 v160, v160, v14
	v_xor_b32_e32 v116, v116, v14
	v_add_u32_e32 v176, v176, v15
	v_xor_b32_e32 v176, v176, v14
	v_xor_b32_e32 v136, v136, v14
	v_add_u32_e32 v178, v178, v15
	v_xor_b32_e32 v178, v178, v14
	v_xor_b32_e32 v174, v174, v14
	v_add_u32_e32 v180, v180, v15
	v_xor_b32_e32 v180, v180, v14
	v_mov_b32_e32 v161, v1
	v_mov_b32_e32 v117, v1
	v_mov_b32_e32 v177, v1
	v_mov_b32_e32 v137, v1
	v_mov_b32_e32 v179, v1
	v_mov_b32_e32 v175, v1
	v_mov_b32_e32 v181, v1
	v_lshl_add_u64 v[186:187], v[0:1], 1, s[38:39]
	v_lshl_add_u64 v[188:189], v[160:161], 1, s[42:43]
	v_lshl_add_u64 v[116:117], v[116:117], 1, s[38:39]
	v_lshl_add_u64 v[176:177], v[176:177], 1, s[42:43]
	v_lshl_add_u64 v[136:137], v[136:137], 1, s[38:39]
	v_lshl_add_u64 v[178:179], v[178:179], 1, s[42:43]
	v_lshl_add_u64 v[174:175], v[174:175], 1, s[38:39]
	v_lshl_add_u64 v[180:181], v[180:181], 1, s[42:43]
	s_add_u32 m0, s100, 0x8000
	s_waitcnt lgkmcnt(6)
	v_mfma_f32_16x16x32_bf16 v[148:151], v[100:103], v[104:107], v[34:37]
	global_load_lds_dwordx4 v2, s[98:99]
	s_waitcnt lgkmcnt(5)
	v_mfma_f32_16x16x32_bf16 v[94:97], v[112:115], v[104:107], v[94:97]
	ds_read_b128 v[152:155], v129
	s_add_u32 m0, s100, 0xc000
	s_waitcnt lgkmcnt(5)
	v_mfma_f32_16x16x32_bf16 v[156:159], v[140:143], v[104:107], v[38:41]
	global_load_lds_dwordx4 v3, s[98:99]
	s_waitcnt lgkmcnt(4)
	v_mfma_f32_16x16x32_bf16 v[90:93], v[144:147], v[104:107], v[90:93]
	ds_read_b128 v[104:107], v129 offset:2048
	s_add_u32 m0, s100, 0x9000
	s_waitcnt lgkmcnt(4)
	v_mfma_f32_16x16x32_bf16 v[160:163], v[100:103], v[108:111], v[42:45]
	global_load_lds_dwordx4 v4, s[98:99]
	v_mfma_f32_16x16x32_bf16 v[86:89], v[112:115], v[108:111], v[86:89]
	ds_read_b128 v[164:167], v129 offset:4096
	s_add_u32 m0, s100, 0xd000
	v_mfma_f32_16x16x32_bf16 v[194:197], v[140:143], v[108:111], v[46:49]
	global_load_lds_dwordx4 v5, s[98:99]
	v_mfma_f32_16x16x32_bf16 v[82:85], v[144:147], v[108:111], v[82:85]
	ds_read_b128 v[108:111], v129 offset:6144
	s_add_u32 m0, s100, 0xa000
	s_waitcnt lgkmcnt(5)
	v_mfma_f32_16x16x32_bf16 v[198:201], v[100:103], v[124:127], v[50:53]
	global_load_lds_dwordx4 v6, s[98:99]
	v_mfma_f32_16x16x32_bf16 v[78:81], v[112:115], v[124:127], v[78:81]
	ds_read_b128 v[202:205], v131 offset:16384
	s_add_u32 m0, s100, 0xe000
	v_mfma_f32_16x16x32_bf16 v[206:209], v[140:143], v[124:127], v[54:57]
	global_load_lds_dwordx4 v7, s[98:99]
	v_mfma_f32_16x16x32_bf16 v[70:73], v[144:147], v[124:127], v[70:73]
	ds_read_b128 v[124:127], v131 offset:18432
	s_add_u32 m0, s100, 0xb000
	s_waitcnt lgkmcnt(6)
	v_mfma_f32_16x16x32_bf16 v[100:103], v[100:103], v[132:135], v[58:61]
	global_load_lds_dwordx4 v8, s[98:99]
	v_mfma_f32_16x16x32_bf16 v[66:69], v[112:115], v[132:135], v[66:69]
	ds_read_b128 v[112:115], v131 offset:20480
	s_add_u32 m0, s100, 0xf000
	v_mfma_f32_16x16x32_bf16 v[140:143], v[140:143], v[132:135], v[62:65]
	global_load_lds_dwordx4 v9, s[98:99]
	v_mfma_f32_16x16x32_bf16 v[74:77], v[144:147], v[132:135], v[74:77]
	ds_read_b128 v[132:135], v131 offset:22528
	s_waitcnt lgkmcnt(3)
	v_mfma_f32_16x16x32_bf16 v[144:147], v[202:205], v[152:155], v[148:151]
	s_waitcnt lgkmcnt(2)
	v_mfma_f32_16x16x32_bf16 v[94:97], v[124:127], v[152:155], v[94:97]
	s_waitcnt lgkmcnt(1)
	v_mfma_f32_16x16x32_bf16 v[148:151], v[112:115], v[152:155], v[156:159]
	s_waitcnt lgkmcnt(0)
	v_mfma_f32_16x16x32_bf16 v[90:93], v[132:135], v[152:155], v[90:93]
	v_mfma_f32_16x16x32_bf16 v[152:155], v[202:205], v[104:107], v[160:163]
	v_mfma_f32_16x16x32_bf16 v[86:89], v[124:127], v[104:107], v[86:89]
	v_mfma_f32_16x16x32_bf16 v[156:159], v[112:115], v[104:107], v[194:197]
	v_mfma_f32_16x16x32_bf16 v[82:85], v[132:135], v[104:107], v[82:85]
	v_mfma_f32_16x16x32_bf16 v[104:107], v[202:205], v[164:167], v[198:201]
	v_mfma_f32_16x16x32_bf16 v[78:81], v[124:127], v[164:167], v[78:81]
	v_mfma_f32_16x16x32_bf16 v[160:163], v[112:115], v[164:167], v[206:209]
	v_mfma_f32_16x16x32_bf16 v[70:73], v[132:135], v[164:167], v[70:73]
	v_mfma_f32_16x16x32_bf16 v[100:103], v[202:205], v[108:111], v[100:103]
	v_mfma_f32_16x16x32_bf16 v[66:69], v[124:127], v[108:111], v[66:69]
	v_mfma_f32_16x16x32_bf16 v[112:115], v[112:115], v[108:111], v[140:143]
	v_mfma_f32_16x16x32_bf16 v[74:77], v[132:135], v[108:111], v[74:77]
	s_waitcnt vmcnt(0)
	s_setprio 0
	s_waitcnt lgkmcnt(0)
	s_barrier
	s_setprio 1
	ds_read_b128 v[26:29], v128 offset:49152
	ds_read_b128 v[10:13], v130 offset:32768
	ds_read_b128 v[30:33], v128 offset:51200
	ds_read_b128 v[132:135], v128 offset:53248
	ds_read_b128 v[140:143], v128 offset:55296
	ds_read_b128 v[18:21], v130 offset:34816
	ds_read_b128 v[108:111], v130 offset:36864
	ds_read_b128 v[124:127], v130 offset:38912
	s_add_u32 m0, s100, 0x0
	s_waitcnt lgkmcnt(6)
	v_mfma_f32_16x16x32_bf16 v[144:147], v[26:29], v[10:13], v[144:147]
	global_load_lds_dwordx4 v[186:187], off
	s_waitcnt lgkmcnt(5)
	v_mfma_f32_16x16x32_bf16 v[94:97], v[30:33], v[10:13], v[94:97]
	ds_read_b128 v[164:167], v129 offset:32768
	s_add_u32 m0, s100, 0x4000
	s_waitcnt lgkmcnt(5)
	v_mfma_f32_16x16x32_bf16 v[148:151], v[132:135], v[10:13], v[148:151]
	global_load_lds_dwordx4 v[188:189], off
	s_waitcnt lgkmcnt(4)
	v_mfma_f32_16x16x32_bf16 v[90:93], v[140:143], v[10:13], v[90:93]
	ds_read_b128 v[194:197], v129 offset:34816
	s_add_u32 m0, s100, 0x1000
	s_waitcnt lgkmcnt(4)
	v_mfma_f32_16x16x32_bf16 v[152:155], v[26:29], v[18:21], v[152:155]
	global_load_lds_dwordx4 v[116:117], off
	v_mfma_f32_16x16x32_bf16 v[86:89], v[30:33], v[18:21], v[86:89]
	ds_read_b128 v[198:201], v129 offset:36864
	s_add_u32 m0, s100, 0x5000
	v_mfma_f32_16x16x32_bf16 v[156:159], v[132:135], v[18:21], v[156:159]
	global_load_lds_dwordx4 v[176:177], off
	v_mfma_f32_16x16x32_bf16 v[82:85], v[140:143], v[18:21], v[82:85]
	ds_read_b128 v[202:205], v129 offset:38912
	s_add_u32 m0, s100, 0x2000
	s_waitcnt lgkmcnt(5)
	v_mfma_f32_16x16x32_bf16 v[104:107], v[26:29], v[108:111], v[104:107]
	global_load_lds_dwordx4 v[136:137], off
	v_mfma_f32_16x16x32_bf16 v[78:81], v[30:33], v[108:111], v[78:81]
	ds_read_b128 v[206:209], v131 offset:49152
	s_add_u32 m0, s100, 0x6000
	v_mfma_f32_16x16x32_bf16 v[160:163], v[132:135], v[108:111], v[160:163]
	global_load_lds_dwordx4 v[178:179], off
	v_mfma_f32_16x16x32_bf16 v[70:73], v[140:143], v[108:111], v[70:73]
	ds_read_b128 v[108:111], v131 offset:51200
	s_add_u32 m0, s100, 0x3000
	s_waitcnt lgkmcnt(6)
	v_mfma_f32_16x16x32_bf16 v[100:103], v[26:29], v[124:127], v[100:103]
	global_load_lds_dwordx4 v[174:175], off
	v_mfma_f32_16x16x32_bf16 v[66:69], v[30:33], v[124:127], v[66:69]
	ds_read_b128 v[210:213], v131 offset:53248
	s_add_u32 m0, s100, 0x7000
	v_mfma_f32_16x16x32_bf16 v[112:115], v[132:135], v[124:127], v[112:115]
	global_load_lds_dwordx4 v[180:181], off
	v_mfma_f32_16x16x32_bf16 v[124:127], v[140:143], v[124:127], v[74:77]
	ds_read_b128 v[128:131], v131 offset:55296
	s_waitcnt lgkmcnt(3)
	v_mfma_f32_16x16x32_bf16 v[132:135], v[206:209], v[164:167], v[144:147]
	s_waitcnt lgkmcnt(2)
	v_mfma_f32_16x16x32_bf16 v[140:143], v[108:111], v[164:167], v[94:97]
	s_waitcnt lgkmcnt(1)
	v_mfma_f32_16x16x32_bf16 v[144:147], v[210:213], v[164:167], v[148:151]
	s_waitcnt lgkmcnt(0)
	v_mfma_f32_16x16x32_bf16 v[148:151], v[128:131], v[164:167], v[90:93]
	v_mfma_f32_16x16x32_bf16 v[152:155], v[206:209], v[194:197], v[152:155]
	v_mfma_f32_16x16x32_bf16 v[164:167], v[108:111], v[194:197], v[86:89]
	v_mfma_f32_16x16x32_bf16 v[156:159], v[210:213], v[194:197], v[156:159]
	v_mfma_f32_16x16x32_bf16 v[194:197], v[128:131], v[194:197], v[82:85]
	v_mfma_f32_16x16x32_bf16 v[94:97], v[206:209], v[198:201], v[104:107]
	v_mfma_f32_16x16x32_bf16 v[86:89], v[108:111], v[198:201], v[78:81]
	v_mfma_f32_16x16x32_bf16 v[90:93], v[210:213], v[198:201], v[160:163]
	v_mfma_f32_16x16x32_bf16 v[82:85], v[128:131], v[198:201], v[70:73]
	v_mfma_f32_16x16x32_bf16 v[74:77], v[206:209], v[202:205], v[100:103]
	v_mfma_f32_16x16x32_bf16 v[66:69], v[108:111], v[202:205], v[66:69]
	v_mfma_f32_16x16x32_bf16 v[70:73], v[210:213], v[202:205], v[112:115]
	v_mfma_f32_16x16x32_bf16 v[78:81], v[128:131], v[202:205], v[124:127]
	s_setprio 0
	v_mul_f32_e32 v0, 0xbfb8aa3b, v132
	v_exp_f32_e32 v0, v0
	v_mul_f32_e32 v99, 0xbfb8aa3b, v133
	v_exp_f32_e32 v99, v99
	v_mul_f32_e32 v101, 0xbfb8aa3b, v135
	v_add_f32_e32 v0, 1.0, v0
	v_rcp_f32_e32 v100, v0
	v_add_f32_e32 v0, 1.0, v99
	v_mul_f32_e32 v99, 0xbfb8aa3b, v134
	v_exp_f32_e32 v99, v99
	v_exp_f32_e32 v103, v101
	v_rcp_f32_e32 v101, v0
	v_mul_f32_e32 v108, 0xbfb8aa3b, v152
	v_add_f32_e32 v0, 1.0, v99
	v_mul_f32_e32 v99, 0xbfb8aa3b, v140
	v_rcp_f32_e32 v102, v0
	v_add_f32_e32 v0, 1.0, v103
	v_exp_f32_e32 v99, v99
	v_mul_f32_e32 v103, 0xbfb8aa3b, v141
	v_exp_f32_e32 v105, v103
	v_rcp_f32_e32 v103, v0
	v_add_f32_e32 v0, 1.0, v99
	v_mul_f32_e32 v99, 0xbfb8aa3b, v142
	v_rcp_f32_e32 v104, v0
	v_add_f32_e32 v0, 1.0, v105
	v_exp_f32_e32 v99, v99
	v_mul_f32_e32 v105, 0xbfb8aa3b, v143
	v_exp_f32_e32 v107, v105
	v_rcp_f32_e32 v105, v0
	v_add_f32_e32 v0, 1.0, v99
	v_rcp_f32_e32 v106, v0
	v_add_f32_e32 v0, 1.0, v107
	v_rcp_f32_e32 v107, v0
	v_pk_mul_f32 v[100:101], v[132:133], v[100:101]
	v_pk_mul_f32 v[102:103], v[134:135], v[102:103]
	v_pk_mul_f32 v[100:101], v[144:145], v[100:101]
	v_pk_mul_f32 v[102:103], v[146:147], v[102:103]
	v_cvt_pk_bf16_f32 v100, v100, v101
	v_cvt_pk_bf16_f32 v101, v102, v103
	v_pk_mul_f32 v[102:103], v[140:141], v[104:105]
	v_pk_mul_f32 v[104:105], v[142:143], v[106:107]
	v_pk_mul_f32 v[102:103], v[148:149], v[102:103]
	v_pk_mul_f32 v[104:105], v[150:151], v[104:105]
	v_add_u32_e32 v0, s4, v118
	v_cvt_pk_bf16_f32 v102, v102, v103
	v_cvt_pk_bf16_f32 v103, v104, v105
	v_mov_b64_e32 v[104:105], s[44:45]
	v_mad_i64_i32 v[106:107], s[14:15], v0, s20, v[104:105]
	v_or_b32_e32 v0, s5, v119
	v_mul_f32_e32 v109, 0xbfb8aa3b, v153
	v_lshl_add_u64 v[106:107], v[106:107], 0, v[0:1]
	v_mov_b32_e32 v99, v1
	v_exp_f32_e32 v108, v108
	v_exp_f32_e32 v109, v109
	v_lshl_add_u64 v[106:107], v[106:107], 0, v[98:99]
	s_barrier
	global_store_dwordx4 v[106:107], v[100:103], off
	v_mul_f32_e32 v106, 0xbfb8aa3b, v164
	v_mul_f32_e32 v107, 0xbfb8aa3b, v165
	v_mul_f32_e32 v102, 0xbfb8aa3b, v154
	v_mul_f32_e32 v103, 0xbfb8aa3b, v155
	v_exp_f32_e32 v102, v102
	v_exp_f32_e32 v103, v103
	v_add_f32_e32 v100, 1.0, v108
	v_add_f32_e32 v101, 1.0, v109
	v_mul_f32_e32 v108, 0xbfb8aa3b, v166
	v_mul_f32_e32 v109, 0xbfb8aa3b, v167
	v_exp_f32_e32 v106, v106
	v_exp_f32_e32 v107, v107
	v_exp_f32_e32 v108, v108
	v_exp_f32_e32 v109, v109
	v_add_f32_e32 v102, 1.0, v102
	v_add_f32_e32 v103, 1.0, v103
	v_rcp_f32_e32 v100, v100
	v_rcp_f32_e32 v101, v101
	v_rcp_f32_e32 v102, v102
	v_rcp_f32_e32 v103, v103
	v_add_f32_e32 v106, 1.0, v106
	v_add_f32_e32 v107, 1.0, v107
	v_add_f32_e32 v108, 1.0, v108
	v_add_f32_e32 v109, 1.0, v109
	v_rcp_f32_e32 v106, v106
	v_rcp_f32_e32 v107, v107
	v_rcp_f32_e32 v108, v108
	v_rcp_f32_e32 v109, v109
	v_pk_mul_f32 v[100:101], v[152:153], v[100:101]
	v_pk_mul_f32 v[102:103], v[154:155], v[102:103]
	v_pk_mul_f32 v[100:101], v[156:157], v[100:101]
	v_pk_mul_f32 v[102:103], v[158:159], v[102:103]
	v_cvt_pk_bf16_f32 v100, v100, v101
	v_cvt_pk_bf16_f32 v101, v102, v103
	v_pk_mul_f32 v[102:103], v[164:165], v[106:107]
	v_pk_mul_f32 v[106:107], v[166:167], v[108:109]
	v_add_u32_e32 v110, s4, v120
	v_pk_mul_f32 v[102:103], v[194:195], v[102:103]
	v_pk_mul_f32 v[106:107], v[196:197], v[106:107]
	v_cvt_pk_bf16_f32 v102, v102, v103
	v_cvt_pk_bf16_f32 v103, v106, v107
	v_mad_i64_i32 v[106:107], s[14:15], v110, s20, v[104:105]
	v_mul_f32_e32 v108, 0xbfb8aa3b, v94
	v_mul_f32_e32 v109, 0xbfb8aa3b, v95
	v_lshl_add_u64 v[106:107], v[106:107], 0, v[0:1]
	v_exp_f32_e32 v108, v108
	v_exp_f32_e32 v109, v109
	v_lshl_add_u64 v[106:107], v[106:107], 0, v[98:99]
	global_store_dwordx4 v[106:107], v[100:103], off
	v_mul_f32_e32 v106, 0xbfb8aa3b, v86
	v_mul_f32_e32 v107, 0xbfb8aa3b, v87
	v_mul_f32_e32 v102, 0xbfb8aa3b, v96
	v_mul_f32_e32 v103, 0xbfb8aa3b, v97
	v_exp_f32_e32 v102, v102
	v_exp_f32_e32 v103, v103
	v_exp_f32_e32 v106, v106
	v_exp_f32_e32 v107, v107
	v_add_f32_e32 v100, 1.0, v108
	v_add_f32_e32 v101, 1.0, v109
	v_mul_f32_e32 v108, 0xbfb8aa3b, v88
	v_mul_f32_e32 v109, 0xbfb8aa3b, v89
	v_exp_f32_e32 v108, v108
	v_exp_f32_e32 v109, v109
	v_rcp_f32_e32 v100, v100
	v_rcp_f32_e32 v101, v101
	v_add_f32_e32 v102, 1.0, v102
	v_add_f32_e32 v103, 1.0, v103
	v_add_f32_e32 v106, 1.0, v106
	v_add_f32_e32 v107, 1.0, v107
	v_rcp_f32_e32 v102, v102
	v_rcp_f32_e32 v103, v103
	v_rcp_f32_e32 v106, v106
	v_rcp_f32_e32 v107, v107
	v_add_f32_e32 v108, 1.0, v108
	v_add_f32_e32 v109, 1.0, v109
	v_rcp_f32_e32 v108, v108
	v_rcp_f32_e32 v109, v109
	v_pk_mul_f32 v[94:95], v[94:95], v[100:101]
	v_pk_mul_f32 v[86:87], v[86:87], v[106:107]
	v_pk_mul_f32 v[90:91], v[90:91], v[94:95]
	v_pk_mul_f32 v[94:95], v[96:97], v[102:103]
	v_pk_mul_f32 v[82:83], v[82:83], v[86:87]
	v_pk_mul_f32 v[92:93], v[92:93], v[94:95]
	v_cvt_pk_bf16_f32 v90, v90, v91
	v_cvt_pk_bf16_f32 v91, v92, v93
	v_cvt_pk_bf16_f32 v92, v82, v83
	v_pk_mul_f32 v[82:83], v[88:89], v[108:109]
	v_add_u32_e32 v110, s4, v121
	v_pk_mul_f32 v[82:83], v[84:85], v[82:83]
	v_mul_f32_e32 v84, 0xbfb8aa3b, v74
	v_mul_f32_e32 v85, 0xbfb8aa3b, v75
	v_exp_f32_e32 v84, v84
	v_exp_f32_e32 v85, v85
	v_cvt_pk_bf16_f32 v93, v82, v83
	v_mad_i64_i32 v[82:83], s[14:15], v110, s20, v[104:105]
	v_lshl_add_u64 v[82:83], v[82:83], 0, v[0:1]
	v_lshl_add_u64 v[82:83], v[82:83], 0, v[98:99]
	global_store_dwordx4 v[82:83], v[90:93], off
	v_add_f32_e32 v82, 1.0, v84
	v_add_f32_e32 v83, 1.0, v85
	v_mul_f32_e32 v84, 0xbfb8aa3b, v76
	v_mul_f32_e32 v85, 0xbfb8aa3b, v77
	v_mul_f32_e32 v86, 0xbfb8aa3b, v66
	v_mul_f32_e32 v87, 0xbfb8aa3b, v67
	v_exp_f32_e32 v84, v84
	v_exp_f32_e32 v85, v85
	v_exp_f32_e32 v86, v86
	v_exp_f32_e32 v87, v87
	v_mul_f32_e32 v88, 0xbfb8aa3b, v68
	v_mul_f32_e32 v89, 0xbfb8aa3b, v69
	v_exp_f32_e32 v88, v88
	v_exp_f32_e32 v89, v89
	v_rcp_f32_e32 v82, v82
	v_rcp_f32_e32 v83, v83
	v_add_f32_e32 v84, 1.0, v84
	v_add_f32_e32 v85, 1.0, v85
	v_add_f32_e32 v86, 1.0, v86
	v_add_f32_e32 v87, 1.0, v87
	v_rcp_f32_e32 v84, v84
	v_rcp_f32_e32 v85, v85
	v_rcp_f32_e32 v86, v86
	v_rcp_f32_e32 v87, v87
	v_add_f32_e32 v88, 1.0, v88
	v_add_f32_e32 v89, 1.0, v89
	v_rcp_f32_e32 v88, v88
	v_rcp_f32_e32 v89, v89
	v_pk_mul_f32 v[74:75], v[74:75], v[82:83]
	v_pk_mul_f32 v[66:67], v[66:67], v[86:87]
	v_pk_mul_f32 v[70:71], v[70:71], v[74:75]
	v_pk_mul_f32 v[74:75], v[76:77], v[84:85]
	v_pk_mul_f32 v[66:67], v[78:79], v[66:67]
	v_pk_mul_f32 v[72:73], v[72:73], v[74:75]
	v_cvt_pk_bf16_f32 v70, v70, v71
	v_cvt_pk_bf16_f32 v71, v72, v73
	v_cvt_pk_bf16_f32 v72, v66, v67
	v_pk_mul_f32 v[66:67], v[68:69], v[88:89]
	v_add_u32_e32 v90, s4, v122
	v_pk_mul_f32 v[66:67], v[80:81], v[66:67]
	s_nop 0
	v_cvt_pk_bf16_f32 v73, v66, v67
	v_mad_i64_i32 v[66:67], s[4:5], v90, s20, v[104:105]
	v_lshl_add_u64 v[66:67], v[66:67], 0, v[0:1]
	v_lshl_add_u64 v[66:67], v[66:67], 0, v[98:99]
	global_store_dwordx4 v[66:67], v[70:73], off
	s_cmp_lg_u32 s101, 0
	s_cbranch_scc0 .LBB0_135

.LBB0_156:
	v_mov_b32_e32 v67, v169
	s_mov_b32 s11, s5
	v_lshrrev_b32_e32 v69, 4, v67
	v_ashrrev_i32_e32 v71, 3, v67
	v_lshrrev_b32_e32 v77, 1, v67
	v_and_b32_e32 v80, 4, v69
	v_and_b32_e32 v81, 3, v71
	v_and_b32_e32 v73, 7, v67
	v_xor_b32_e32 v75, v71, v67
	v_and_b32_e32 v77, 16, v77
	v_and_b32_e32 v79, 8, v69
	v_or_b32_e32 v82, v80, v81
	v_lshlrev_b32_e32 v75, 4, v75
	v_or3_b32 v77, v77, v79, v82
	v_bitop3_b32 v79, v80, v73, v81 bitop3:0x36
	v_lshlrev_b32_e32 v71, 7, v71
	v_lshlrev_b32_e32 v79, 4, v79
	v_and_or_b32 v117, v75, s24, v71
	v_lshl_or_b32 v116, v77, 7, v79
	v_lshlrev_b32_e32 v34, 7, v67
	v_and_b32_e32 v35, 0x780, v34
	v_and_b32_e32 v118, 0x2780, v34
	v_bitop3_b32 v34, v69, v73, 3 bitop3:0x6c
	v_bfe_u32 v77, v67, 4, 2
	v_lshlrev_b32_e32 v119, 4, v34
	v_lshlrev_b32_e32 v34, 6, v67
	v_mov_b32_e32 v75, v1
	v_and_or_b32 v120, v34, s30, v35
	v_bitop3_b32 v34, v77, v73, 4 bitop3:0x36
	v_mov_b32_e32 v73, v1
	v_mov_b32_e32 v67, v1
	v_mov_b32_e32 v69, v1
	v_mov_b32_e32 v77, v1
	v_mov_b32_e32 v71, v1
	v_mov_b32_e32 v79, v1
	v_lshl_add_u64 v[100:101], v[74:75], 1, s[28:29]
	s_mov_b32 s10, s9
	s_mov_b32 s4, s8
	v_lshlrev_b32_e32 v121, 4, v34
	v_lshl_add_u64 v[98:99], v[72:73], 1, s[28:29]
	v_lshl_add_u64 v[102:103], v[76:77], 1, s[28:29]
	v_lshl_add_u64 v[104:105], v[78:79], 1, s[28:29]
	v_lshlrev_b64 v[106:107], 1, v[0:1]
	v_lshlrev_b64 v[108:109], 1, v[66:67]
	v_lshlrev_b64 v[110:111], 1, v[68:69]
	v_lshlrev_b64 v[112:113], 1, v[70:71]
	s_mov_b32 s5, -2
	s_mov_b64 s[38:39], s[72:73]
	s_waitcnt vmcnt(4)
	s_waitcnt lgkmcnt(0)
	s_barrier
	v_lshrrev_b32_e32 v222, 6, v169
	v_lshlrev_b32_e32 v222, 10, v222
	v_lshrrev_b32_e32 v223, 3, v169
	v_readfirstlane_b32 s100, v222
	v_and_b32_e32 v222, 3, v223
	v_bfe_u32 v224, v223, 4, 1
	v_lshl_or_b32 v222, v224, 2, v222
	v_bfe_u32 v224, v223, 2, 1
	v_lshl_or_b32 v222, v224, 3, v222
	v_bfe_u32 v224, v223, 3, 1
	v_lshl_or_b32 v222, v224, 4, v222
	v_sub_u32_e32 v222, v222, v223
	v_mul_i32_i24_e32 v222, 0x800, v222
	v_and_b32_e32 v223, 7, v223
	v_lshlrev_b32_e32 v223, 4, v223
	v_add_u32_e32 v210, 0xef11000, v106
	v_xor_b32_e32 v194, v210, v223
	v_mov_b32_e32 v211, v98
	v_add_u32_e32 v195, v211, v222
	v_xor_b32_e32 v195, v195, v223
	v_add_u32_e32 v212, 0xef11000, v108
	v_xor_b32_e32 v196, v212, v223
	v_mov_b32_e32 v213, v100
	v_add_u32_e32 v197, v213, v222
	v_xor_b32_e32 v197, v197, v223
	v_add_u32_e32 v218, 0xef11000, v110
	v_xor_b32_e32 v202, v218, v223
	v_mov_b32_e32 v219, v102
	v_add_u32_e32 v203, v219, v222
	v_xor_b32_e32 v203, v203, v223
	v_add_u32_e32 v220, 0xef11000, v112
	v_xor_b32_e32 v204, v220, v223
	v_mov_b32_e32 v221, v104
	v_add_u32_e32 v205, v221, v222
	v_xor_b32_e32 v205, v205, v223
	s_setprio 1
	s_add_u32 s98, s38, s36
	s_addc_u32 s99, s39, 0
	s_add_u32 s98, s98, 0x80
	s_addc_u32 s99, s99, 0
	v_add_u32_e32 v122, v119, v118
	v_add_u32_e32 v124, v119, v120
	v_add_u32_e32 v123, v121, v120
	ds_read_b128 v[126:129], v122 offset:16384
	ds_read_b128 v[130:133], v124
	ds_read_b128 v[144:147], v122 offset:18432
	ds_read_b128 v[158:161], v122 offset:20480
	ds_read_b128 v[162:165], v122 offset:22528
	ds_read_b128 v[134:137], v124 offset:2048
	ds_read_b128 v[140:143], v124 offset:4096
	ds_read_b128 v[148:151], v124 offset:6144
	s_add_u32 m0, s100, 0x8000
	s_waitcnt lgkmcnt(6)
	v_mfma_f32_16x16x32_bf16 v[34:37], v[126:129], v[130:133], 0
	global_load_lds_dwordx4 v194, s[98:99]
	s_waitcnt lgkmcnt(5)
	v_mfma_f32_16x16x32_bf16 v[94:97], v[144:147], v[130:133], 0
	ds_read_b128 v[198:201], v123
	s_add_u32 m0, s100, 0xc000
	s_waitcnt lgkmcnt(5)
	v_mfma_f32_16x16x32_bf16 v[38:41], v[158:161], v[130:133], 0
	global_load_lds_dwordx4 v195, s[98:99]
	s_waitcnt lgkmcnt(4)
	v_mfma_f32_16x16x32_bf16 v[90:93], v[162:165], v[130:133], 0
	ds_read_b128 v[206:209], v123 offset:2048
	s_add_u32 m0, s100, 0x9000
	s_waitcnt lgkmcnt(4)
	v_mfma_f32_16x16x32_bf16 v[42:45], v[126:129], v[134:137], 0
	global_load_lds_dwordx4 v196, s[98:99]
	v_mfma_f32_16x16x32_bf16 v[86:89], v[144:147], v[134:137], 0
	ds_read_b128 v[214:217], v123 offset:4096
	s_add_u32 m0, s100, 0xd000
	v_mfma_f32_16x16x32_bf16 v[46:49], v[158:161], v[134:137], 0
	global_load_lds_dwordx4 v197, s[98:99]
	v_mfma_f32_16x16x32_bf16 v[82:85], v[162:165], v[134:137], 0
	v_add_u32_e32 v130, v121, v118
	ds_read_b128 v[132:135], v123 offset:6144
	s_add_u32 m0, s100, 0xa000
	s_waitcnt lgkmcnt(5)
	v_mfma_f32_16x16x32_bf16 v[50:53], v[126:129], v[140:143], 0
	global_load_lds_dwordx4 v202, s[98:99]
	v_mfma_f32_16x16x32_bf16 v[78:81], v[144:147], v[140:143], 0
	ds_read_b128 v[226:229], v130 offset:16384
	s_add_u32 m0, s100, 0xe000
	v_mfma_f32_16x16x32_bf16 v[54:57], v[158:161], v[140:143], 0
	global_load_lds_dwordx4 v203, s[98:99]
	v_mfma_f32_16x16x32_bf16 v[70:73], v[162:165], v[140:143], 0
	ds_read_b128 v[140:143], v130 offset:18432
	s_add_u32 m0, s100, 0xb000
	s_waitcnt lgkmcnt(6)
	v_mfma_f32_16x16x32_bf16 v[58:61], v[126:129], v[148:151], 0
	global_load_lds_dwordx4 v204, s[98:99]
	v_mfma_f32_16x16x32_bf16 v[66:69], v[144:147], v[148:151], 0
	ds_read_b128 v[144:147], v130 offset:20480
	s_add_u32 m0, s100, 0xf000
	v_mfma_f32_16x16x32_bf16 v[62:65], v[158:161], v[148:151], 0
	global_load_lds_dwordx4 v205, s[98:99]
	v_mfma_f32_16x16x32_bf16 v[74:77], v[162:165], v[148:151], 0
	ds_read_b128 v[148:151], v130 offset:22528
	s_waitcnt lgkmcnt(3)
	v_mfma_f32_16x16x32_bf16 v[34:37], v[226:229], v[198:201], v[34:37]
	s_waitcnt lgkmcnt(2)
	v_mfma_f32_16x16x32_bf16 v[94:97], v[140:143], v[198:201], v[94:97]
	s_waitcnt lgkmcnt(1)
	v_mfma_f32_16x16x32_bf16 v[38:41], v[144:147], v[198:201], v[38:41]
	s_waitcnt lgkmcnt(0)
	v_mfma_f32_16x16x32_bf16 v[90:93], v[148:151], v[198:201], v[90:93]
	v_mfma_f32_16x16x32_bf16 v[42:45], v[226:229], v[206:209], v[42:45]
	v_mfma_f32_16x16x32_bf16 v[86:89], v[140:143], v[206:209], v[86:89]
	v_mfma_f32_16x16x32_bf16 v[46:49], v[144:147], v[206:209], v[46:49]
	v_mfma_f32_16x16x32_bf16 v[82:85], v[148:151], v[206:209], v[82:85]
	v_mfma_f32_16x16x32_bf16 v[50:53], v[226:229], v[214:217], v[50:53]
	v_mfma_f32_16x16x32_bf16 v[78:81], v[140:143], v[214:217], v[78:81]
	v_mfma_f32_16x16x32_bf16 v[54:57], v[144:147], v[214:217], v[54:57]
	v_mfma_f32_16x16x32_bf16 v[70:73], v[148:151], v[214:217], v[70:73]
	v_mfma_f32_16x16x32_bf16 v[58:61], v[226:229], v[132:135], v[58:61]
	v_mfma_f32_16x16x32_bf16 v[66:69], v[140:143], v[132:135], v[66:69]
	v_mfma_f32_16x16x32_bf16 v[62:65], v[144:147], v[132:135], v[62:65]
	v_mfma_f32_16x16x32_bf16 v[74:77], v[148:151], v[132:135], v[74:77]
	s_waitcnt vmcnt(0)
	s_setprio 0
	s_waitcnt lgkmcnt(0)
	s_barrier
	s_branch .Lk3_odd_157

.Lk3_odd_157:
	s_setprio 1
	s_add_u32 s98, s98, 0x80
	s_addc_u32 s99, s99, 0
	ds_read_b128 v[26:29], v122 offset:49152
	ds_read_b128 v[10:13], v124 offset:32768
	ds_read_b128 v[30:33], v122 offset:51200
	ds_read_b128 v[144:147], v122 offset:53248
	ds_read_b128 v[148:151], v122 offset:55296
	ds_read_b128 v[18:21], v124 offset:34816
	ds_read_b128 v[132:135], v124 offset:36864
	ds_read_b128 v[140:143], v124 offset:38912
	s_add_u32 m0, s100, 0x0
	s_waitcnt lgkmcnt(6)
	v_mfma_f32_16x16x32_bf16 v[34:37], v[26:29], v[10:13], v[34:37]
	global_load_lds_dwordx4 v194, s[98:99]
	s_waitcnt lgkmcnt(5)
	v_mfma_f32_16x16x32_bf16 v[94:97], v[30:33], v[10:13], v[94:97]
	ds_read_b128 v[162:165], v123 offset:32768
	s_add_u32 m0, s100, 0x4000
	s_waitcnt lgkmcnt(5)
	v_mfma_f32_16x16x32_bf16 v[38:41], v[144:147], v[10:13], v[38:41]
	global_load_lds_dwordx4 v195, s[98:99]
	s_waitcnt lgkmcnt(4)
	v_mfma_f32_16x16x32_bf16 v[90:93], v[148:151], v[10:13], v[90:93]
	ds_read_b128 v[198:201], v123 offset:34816
	s_add_u32 m0, s100, 0x1000
	s_waitcnt lgkmcnt(4)
	v_mfma_f32_16x16x32_bf16 v[42:45], v[26:29], v[18:21], v[42:45]
	global_load_lds_dwordx4 v196, s[98:99]
	v_mfma_f32_16x16x32_bf16 v[86:89], v[30:33], v[18:21], v[86:89]
	ds_read_b128 v[206:209], v123 offset:36864
	s_add_u32 m0, s100, 0x5000
	v_mfma_f32_16x16x32_bf16 v[46:49], v[144:147], v[18:21], v[46:49]
	global_load_lds_dwordx4 v197, s[98:99]
	v_mfma_f32_16x16x32_bf16 v[82:85], v[148:151], v[18:21], v[82:85]
	ds_read_b128 v[214:217], v123 offset:38912
	s_add_u32 m0, s100, 0x2000
	s_waitcnt lgkmcnt(5)
	v_mfma_f32_16x16x32_bf16 v[50:53], v[26:29], v[132:135], v[50:53]
	global_load_lds_dwordx4 v202, s[98:99]
	v_mfma_f32_16x16x32_bf16 v[78:81], v[30:33], v[132:135], v[78:81]
	ds_read_b128 v[226:229], v130 offset:49152
	s_add_u32 m0, s100, 0x6000
	v_mfma_f32_16x16x32_bf16 v[54:57], v[144:147], v[132:135], v[54:57]
	global_load_lds_dwordx4 v203, s[98:99]
	v_mfma_f32_16x16x32_bf16 v[70:73], v[148:151], v[132:135], v[70:73]
	ds_read_b128 v[132:135], v130 offset:51200
	s_add_u32 m0, s100, 0x3000
	s_waitcnt lgkmcnt(6)
	v_mfma_f32_16x16x32_bf16 v[58:61], v[26:29], v[140:143], v[58:61]
	global_load_lds_dwordx4 v204, s[98:99]
	v_mfma_f32_16x16x32_bf16 v[66:69], v[30:33], v[140:143], v[66:69]
	ds_read_b128 v[234:237], v130 offset:53248
	s_add_u32 m0, s100, 0x7000
	v_mfma_f32_16x16x32_bf16 v[62:65], v[144:147], v[140:143], v[62:65]
	global_load_lds_dwordx4 v205, s[98:99]
	v_mfma_f32_16x16x32_bf16 v[74:77], v[148:151], v[140:143], v[74:77]
	ds_read_b128 v[140:143], v130 offset:55296
	s_waitcnt lgkmcnt(3)
	v_mfma_f32_16x16x32_bf16 v[34:37], v[226:229], v[162:165], v[34:37]
	s_waitcnt lgkmcnt(2)
	v_mfma_f32_16x16x32_bf16 v[94:97], v[132:135], v[162:165], v[94:97]
	s_waitcnt lgkmcnt(1)
	v_mfma_f32_16x16x32_bf16 v[38:41], v[234:237], v[162:165], v[38:41]
	s_waitcnt lgkmcnt(0)
	v_mfma_f32_16x16x32_bf16 v[90:93], v[140:143], v[162:165], v[90:93]
	v_mfma_f32_16x16x32_bf16 v[42:45], v[226:229], v[198:201], v[42:45]
	v_mfma_f32_16x16x32_bf16 v[86:89], v[132:135], v[198:201], v[86:89]
	v_mfma_f32_16x16x32_bf16 v[46:49], v[234:237], v[198:201], v[46:49]
	v_mfma_f32_16x16x32_bf16 v[82:85], v[140:143], v[198:201], v[82:85]
	v_mfma_f32_16x16x32_bf16 v[50:53], v[226:229], v[206:209], v[50:53]
	v_mfma_f32_16x16x32_bf16 v[78:81], v[132:135], v[206:209], v[78:81]
	v_mfma_f32_16x16x32_bf16 v[54:57], v[234:237], v[206:209], v[54:57]
	v_mfma_f32_16x16x32_bf16 v[70:73], v[140:143], v[206:209], v[70:73]
	v_mfma_f32_16x16x32_bf16 v[58:61], v[226:229], v[214:217], v[58:61]
	v_mfma_f32_16x16x32_bf16 v[66:69], v[132:135], v[214:217], v[66:69]
	v_mfma_f32_16x16x32_bf16 v[62:65], v[234:237], v[214:217], v[62:65]
	v_mfma_f32_16x16x32_bf16 v[74:77], v[140:143], v[214:217], v[74:77]
	s_waitcnt vmcnt(0)
	s_setprio 0
	s_add_i32 s5, s5, 2
	s_add_u32 s38, s38, 0x100
	s_addc_u32 s39, s39, 0
	s_cmp_lt_u32 s5, 12
	s_waitcnt lgkmcnt(0)
	s_barrier
	s_cbranch_scc1 .LBB0_157
	v_mov_b32_e32 v2, v194
	v_mov_b32_e32 v3, v195
	v_mov_b32_e32 v4, v196
	v_mov_b32_e32 v5, v197
	v_mov_b32_e32 v6, v202
	v_mov_b32_e32 v7, v203
	v_mov_b32_e32 v8, v204
	v_mov_b32_e32 v9, v205
	s_add_u32 s98, s38, s36
	s_addc_u32 s99, s39, 0
	s_add_u32 s98, s98, 0x80
	s_addc_u32 s99, s99, 0
	s_add_i32 s5, s11, s2
	s_cmpk_lt_u32 s5, 0x100
	s_cselect_b64 s[44:45], -1, 0
	s_and_b64 s[8:9], s[44:45], exec
	s_cselect_b32 s9, s5, s11
	s_lshr_b32 s8, s9, 3
	s_and_b32 s8, s8, 0x1fffff8
	s_add_i32 s8, s8, s21
	s_and_b32 s11, s9, 7
	v_mov_b32_e32 v0, v169
	s_or_b32 s8, s8, s11
	s_lshl_b32 s8, s8, 7
	v_lshrrev_b32_e32 v98, 3, v0
	v_lshlrev_b32_e32 v0, 3, v0
	v_add_u32_e32 v98, s8, v98
	v_and_b32_e32 v0, 56, v0
	v_lshl_or_b32 v0, v98, 10, v0
	v_mov_b32_e32 v98, v169
	s_lshl_b32 s9, s9, 4
	s_and_b32 s9, s9, 0x380
	v_lshrrev_b32_e32 v99, 3, v98
	v_lshlrev_b32_e32 v98, 3, v98
	v_add_u32_e32 v99, s9, v99
	v_and_b32_e32 v98, 56, v98
	v_add_u32_e32 v114, 0x8000, v0
	v_add_u32_e32 v136, 0x10000, v0
	v_lshl_or_b32 v162, v99, 10, v98
	v_add_u32_e32 v166, 0x18000, v0
	v_add_u32_e32 v174, 0x8000, v162
	v_add_u32_e32 v176, 0x10000, v162
	v_add_u32_e32 v178, 0x18000, v162
	s_setprio 1
	ds_read_b128 v[98:101], v122 offset:16384
	ds_read_b128 v[102:105], v124
	ds_read_b128 v[110:113], v122 offset:18432
	ds_read_b128 v[132:135], v122 offset:20480
	ds_read_b128 v[140:143], v122 offset:22528
	ds_read_b128 v[106:109], v124 offset:2048
	ds_read_b128 v[118:121], v124 offset:4096
	ds_read_b128 v[126:129], v124 offset:6144
	v_lshrrev_b32_e32 v14, 3, v169
	v_and_b32_e32 v15, 3, v14
	v_bfe_u32 v16, v14, 4, 1
	v_lshl_or_b32 v15, v16, 2, v15
	v_bfe_u32 v16, v14, 2, 1
	v_lshl_or_b32 v15, v16, 3, v15
	v_bfe_u32 v16, v14, 3, 1
	v_lshl_or_b32 v15, v16, 4, v15
	v_sub_u32_e32 v15, v15, v14
	v_mul_i32_i24_e32 v15, 0x400, v15
	v_and_b32_e32 v14, 7, v14
	v_lshlrev_b32_e32 v14, 3, v14
	v_xor_b32_e32 v0, v0, v14
	v_add_u32_e32 v162, v162, v15
	v_xor_b32_e32 v162, v162, v14
	v_xor_b32_e32 v114, v114, v14
	v_add_u32_e32 v174, v174, v15
	v_xor_b32_e32 v174, v174, v14
	v_xor_b32_e32 v136, v136, v14
	v_add_u32_e32 v176, v176, v15
	v_xor_b32_e32 v176, v176, v14
	v_xor_b32_e32 v166, v166, v14
	v_add_u32_e32 v178, v178, v15
	v_xor_b32_e32 v178, v178, v14
	v_readlane_b32 s14, v254, 45
	v_readlane_b32 s15, v254, 46
	v_mov_b32_e32 v163, v1
	v_mov_b32_e32 v115, v1
	v_mov_b32_e32 v175, v1
	v_mov_b32_e32 v137, v1
	v_mov_b32_e32 v177, v1
	v_mov_b32_e32 v167, v1
	v_mov_b32_e32 v179, v1
	v_lshl_add_u64 v[180:181], v[0:1], 1, s[14:15]
	v_lshl_add_u64 v[186:187], v[162:163], 1, s[34:35]
	v_lshl_add_u64 v[188:189], v[114:115], 1, s[14:15]
	v_lshl_add_u64 v[174:175], v[174:175], 1, s[34:35]
	v_lshl_add_u64 v[136:137], v[136:137], 1, s[14:15]
	v_lshl_add_u64 v[176:177], v[176:177], 1, s[34:35]
	v_lshl_add_u64 v[166:167], v[166:167], 1, s[14:15]
	v_lshl_add_u64 v[178:179], v[178:179], 1, s[34:35]
	s_add_u32 m0, s100, 0x8000
	s_waitcnt lgkmcnt(6)
	v_mfma_f32_16x16x32_bf16 v[144:147], v[98:101], v[102:105], v[34:37]
	global_load_lds_dwordx4 v2, s[98:99]
	s_waitcnt lgkmcnt(5)
	v_mfma_f32_16x16x32_bf16 v[94:97], v[110:113], v[102:105], v[94:97]
	ds_read_b128 v[148:151], v123
	s_add_u32 m0, s100, 0xc000
	s_waitcnt lgkmcnt(5)
	v_mfma_f32_16x16x32_bf16 v[158:161], v[132:135], v[102:105], v[38:41]
	global_load_lds_dwordx4 v3, s[98:99]
	s_waitcnt lgkmcnt(4)
	v_mfma_f32_16x16x32_bf16 v[90:93], v[140:143], v[102:105], v[90:93]
	ds_read_b128 v[102:105], v123 offset:2048
	s_add_u32 m0, s100, 0x9000
	s_waitcnt lgkmcnt(4)
	v_mfma_f32_16x16x32_bf16 v[162:165], v[98:101], v[106:109], v[42:45]
	global_load_lds_dwordx4 v4, s[98:99]
	v_mfma_f32_16x16x32_bf16 v[86:89], v[110:113], v[106:109], v[86:89]
	ds_read_b128 v[194:197], v123 offset:4096
	s_add_u32 m0, s100, 0xd000
	v_mfma_f32_16x16x32_bf16 v[198:201], v[132:135], v[106:109], v[46:49]
	global_load_lds_dwordx4 v5, s[98:99]
	v_mfma_f32_16x16x32_bf16 v[82:85], v[140:143], v[106:109], v[82:85]
	ds_read_b128 v[106:109], v123 offset:6144
	s_add_u32 m0, s100, 0xa000
	s_waitcnt lgkmcnt(5)
	v_mfma_f32_16x16x32_bf16 v[202:205], v[98:101], v[118:121], v[50:53]
	global_load_lds_dwordx4 v6, s[98:99]
	v_mfma_f32_16x16x32_bf16 v[78:81], v[110:113], v[118:121], v[78:81]
	ds_read_b128 v[206:209], v130 offset:16384
	s_add_u32 m0, s100, 0xe000
	v_mfma_f32_16x16x32_bf16 v[210:213], v[132:135], v[118:121], v[54:57]
	global_load_lds_dwordx4 v7, s[98:99]
	v_mfma_f32_16x16x32_bf16 v[70:73], v[140:143], v[118:121], v[70:73]
	ds_read_b128 v[118:121], v130 offset:18432
	s_add_u32 m0, s100, 0xb000
	s_waitcnt lgkmcnt(6)
	v_mfma_f32_16x16x32_bf16 v[98:101], v[98:101], v[126:129], v[58:61]
	global_load_lds_dwordx4 v8, s[98:99]
	v_mfma_f32_16x16x32_bf16 v[66:69], v[110:113], v[126:129], v[66:69]
	ds_read_b128 v[110:113], v130 offset:20480
	s_add_u32 m0, s100, 0xf000
	v_mfma_f32_16x16x32_bf16 v[132:135], v[132:135], v[126:129], v[62:65]
	global_load_lds_dwordx4 v9, s[98:99]
	v_mfma_f32_16x16x32_bf16 v[74:77], v[140:143], v[126:129], v[74:77]
	ds_read_b128 v[126:129], v130 offset:22528
	s_waitcnt lgkmcnt(3)
	v_mfma_f32_16x16x32_bf16 v[140:143], v[206:209], v[148:151], v[144:147]
	s_waitcnt lgkmcnt(2)
	v_mfma_f32_16x16x32_bf16 v[94:97], v[118:121], v[148:151], v[94:97]
	s_waitcnt lgkmcnt(1)
	v_mfma_f32_16x16x32_bf16 v[144:147], v[110:113], v[148:151], v[158:161]
	s_waitcnt lgkmcnt(0)
	v_mfma_f32_16x16x32_bf16 v[90:93], v[126:129], v[148:151], v[90:93]
	v_mfma_f32_16x16x32_bf16 v[148:151], v[206:209], v[102:105], v[162:165]
	v_mfma_f32_16x16x32_bf16 v[86:89], v[118:121], v[102:105], v[86:89]
	v_mfma_f32_16x16x32_bf16 v[158:161], v[110:113], v[102:105], v[198:201]
	v_mfma_f32_16x16x32_bf16 v[82:85], v[126:129], v[102:105], v[82:85]
	v_mfma_f32_16x16x32_bf16 v[102:105], v[206:209], v[194:197], v[202:205]
	v_mfma_f32_16x16x32_bf16 v[78:81], v[118:121], v[194:197], v[78:81]
	v_mfma_f32_16x16x32_bf16 v[162:165], v[110:113], v[194:197], v[210:213]
	v_mfma_f32_16x16x32_bf16 v[70:73], v[126:129], v[194:197], v[70:73]
	v_mfma_f32_16x16x32_bf16 v[98:101], v[206:209], v[106:109], v[98:101]
	v_mfma_f32_16x16x32_bf16 v[66:69], v[118:121], v[106:109], v[66:69]
	v_mfma_f32_16x16x32_bf16 v[110:113], v[110:113], v[106:109], v[132:135]
	v_mfma_f32_16x16x32_bf16 v[74:77], v[126:129], v[106:109], v[74:77]
	s_waitcnt vmcnt(0)
	s_setprio 0
	s_waitcnt lgkmcnt(0)
	s_barrier
	s_setprio 1
	ds_read_b128 v[26:29], v122 offset:49152
	ds_read_b128 v[10:13], v124 offset:32768
	ds_read_b128 v[18:21], v124 offset:34816
	ds_read_b128 v[30:33], v122 offset:51200
	ds_read_b128 v[106:109], v124 offset:36864
	ds_read_b128 v[114:117], v124 offset:38912
	ds_read_b128 v[118:121], v122 offset:53248
	ds_read_b128 v[124:127], v122 offset:55296
	s_add_u32 m0, s100, 0x0
	s_waitcnt lgkmcnt(6)
	v_mfma_f32_16x16x32_bf16 v[132:135], v[26:29], v[10:13], v[140:143]
	global_load_lds_dwordx4 v[180:181], off
	s_waitcnt lgkmcnt(4)
	v_mfma_f32_16x16x32_bf16 v[94:97], v[30:33], v[10:13], v[94:97]
	ds_read_b128 v[140:143], v123 offset:32768
	s_add_u32 m0, s100, 0x4000
	s_waitcnt lgkmcnt(2)
	v_mfma_f32_16x16x32_bf16 v[144:147], v[118:121], v[10:13], v[144:147]
	global_load_lds_dwordx4 v[186:187], off
	s_waitcnt lgkmcnt(1)
	v_mfma_f32_16x16x32_bf16 v[90:93], v[124:127], v[10:13], v[90:93]
	ds_read_b128 v[194:197], v123 offset:34816
	s_add_u32 m0, s100, 0x1000
	v_mfma_f32_16x16x32_bf16 v[148:151], v[26:29], v[18:21], v[148:151]
	global_load_lds_dwordx4 v[188:189], off
	v_mfma_f32_16x16x32_bf16 v[86:89], v[30:33], v[18:21], v[86:89]
	ds_read_b128 v[198:201], v123 offset:36864
	s_add_u32 m0, s100, 0x5000
	v_mfma_f32_16x16x32_bf16 v[158:161], v[118:121], v[18:21], v[158:161]
	global_load_lds_dwordx4 v[174:175], off
	v_mfma_f32_16x16x32_bf16 v[82:85], v[124:127], v[18:21], v[82:85]
	ds_read_b128 v[202:205], v123 offset:38912
	s_add_u32 m0, s100, 0x2000
	v_mfma_f32_16x16x32_bf16 v[206:209], v[26:29], v[106:109], v[102:105]
	global_load_lds_dwordx4 v[136:137], off
	v_mfma_f32_16x16x32_bf16 v[78:81], v[30:33], v[106:109], v[78:81]
	ds_read_b128 v[210:213], v130 offset:49152
	s_add_u32 m0, s100, 0x6000
	v_mfma_f32_16x16x32_bf16 v[162:165], v[118:121], v[106:109], v[162:165]
	global_load_lds_dwordx4 v[176:177], off
	v_mfma_f32_16x16x32_bf16 v[70:73], v[124:127], v[106:109], v[70:73]
	ds_read_b128 v[214:217], v130 offset:51200
	s_add_u32 m0, s100, 0x3000
	v_mfma_f32_16x16x32_bf16 v[218:221], v[26:29], v[114:117], v[98:101]
	global_load_lds_dwordx4 v[166:167], off
	v_mfma_f32_16x16x32_bf16 v[66:69], v[30:33], v[114:117], v[66:69]
	ds_read_b128 v[222:225], v130 offset:53248
	s_add_u32 m0, s100, 0x7000
	v_mfma_f32_16x16x32_bf16 v[226:229], v[118:121], v[114:117], v[110:113]
	global_load_lds_dwordx4 v[178:179], off
	v_mfma_f32_16x16x32_bf16 v[230:233], v[124:127], v[114:117], v[74:77]
	s_waitcnt lgkmcnt(2)
	v_mfma_f32_16x16x32_bf16 v[126:129], v[210:213], v[140:143], v[132:135]
	ds_read_b128 v[130:133], v130 offset:55296
	s_waitcnt lgkmcnt(2)
	v_mfma_f32_16x16x32_bf16 v[122:125], v[214:217], v[140:143], v[94:97]
	s_waitcnt lgkmcnt(1)
	v_mfma_f32_16x16x32_bf16 v[118:121], v[222:225], v[140:143], v[144:147]
	s_waitcnt lgkmcnt(0)
	v_mfma_f32_16x16x32_bf16 v[114:117], v[130:133], v[140:143], v[90:93]
	v_mfma_f32_16x16x32_bf16 v[110:113], v[210:213], v[194:197], v[148:151]
	v_mfma_f32_16x16x32_bf16 v[106:109], v[214:217], v[194:197], v[86:89]
	v_mfma_f32_16x16x32_bf16 v[102:105], v[222:225], v[194:197], v[158:161]
	v_mfma_f32_16x16x32_bf16 v[98:101], v[130:133], v[194:197], v[82:85]
	v_mfma_f32_16x16x32_bf16 v[94:97], v[210:213], v[198:201], v[206:209]
	v_mfma_f32_16x16x32_bf16 v[90:93], v[214:217], v[198:201], v[78:81]
	v_mfma_f32_16x16x32_bf16 v[86:89], v[222:225], v[198:201], v[162:165]
	v_mfma_f32_16x16x32_bf16 v[82:85], v[130:133], v[198:201], v[70:73]
	v_mfma_f32_16x16x32_bf16 v[78:81], v[210:213], v[202:205], v[218:221]
	v_mfma_f32_16x16x32_bf16 v[74:77], v[214:217], v[202:205], v[66:69]
	v_mfma_f32_16x16x32_bf16 v[70:73], v[222:225], v[202:205], v[226:229]
	v_mfma_f32_16x16x32_bf16 v[66:69], v[130:133], v[202:205], v[230:233]
	s_setprio 0
	v_add_u32_e32 v134, s4, v152
	v_ashrrev_i32_e32 v135, 31, v134
	v_lshlrev_b64 v[136:137], 12, v[134:135]
	v_or_b32_e32 v140, s10, v153
	v_mov_b32_e32 v141, v1
	v_cndmask_b32_e64 v0, 0, 1, s[42:43]
	v_lshl_add_u64 v[130:131], s[40:41], 0, v[136:137]
	v_cmp_ne_u32_e64 s[38:39], 1, v0
	s_andn2_b64 vcc, exec, s[42:43]
	v_lshl_add_u64 v[146:147], v[140:141], 2, v[130:131]
	s_barrier
	v_readlane_b32 s48, v253, 18
	v_readlane_b32 s49, v253, 19
	v_readlane_b32 s50, v253, 20
	v_readlane_b32 s51, v253, 21
	v_readlane_b32 s52, v253, 22
	v_readlane_b32 s53, v253, 23
	v_readlane_b32 s54, v253, 24
	v_readlane_b32 s55, v253, 25
	v_readlane_b32 s56, v253, 26
	v_readlane_b32 s57, v253, 27
	v_readlane_b32 s58, v253, 28
	v_readlane_b32 s59, v253, 29
	v_readlane_b32 s60, v253, 30
	v_readlane_b32 s61, v253, 31
	v_readlane_b32 s62, v253, 32
	v_readlane_b32 s63, v253, 33
	v_or_b32_e32 v0, s10, v153
	v_lshlrev_b32_e32 v0, 2, v0
	v_add_u32_e32 v130, s4, v152
	v_lshlrev_b32_e32 v50, 3, v130
	v_lshlrev_b32_e32 v130, 12, v130
	v_add_u32_e32 v130, v130, v0
	v_add_u32_e32 v131, s4, v154
	v_lshlrev_b32_e32 v54, 3, v131
	v_lshlrev_b32_e32 v131, 12, v131
	v_add_u32_e32 v131, v131, v0
	v_add_u32_e32 v132, s4, v155
	v_lshlrev_b32_e32 v58, 3, v132
	v_lshlrev_b32_e32 v132, 12, v132
	v_add_u32_e32 v132, v132, v0
	v_add_u32_e32 v133, s4, v156
	v_lshlrev_b32_e32 v62, 3, v133
	v_lshlrev_b32_e32 v133, 12, v133
	v_add_u32_e32 v133, v133, v0
	s_mov_b32 s10, 0x3fb504f3
	s_cmp_lg_u64 s[40:41], 0
	s_cbranch_scc0 .Lepi_ln_157
	global_load_dwordx4 v[2:5], v130, s[40:41]
	global_load_dwordx4 v[6:9], v131, s[40:41]
	global_load_dwordx4 v[10:13], v132, s[40:41]
	global_load_dwordx4 v[14:17], v133, s[40:41]
	global_load_dwordx4 v[18:21], v130, s[40:41] offset:16
	global_load_dwordx4 v[22:25], v131, s[40:41] offset:16
	global_load_dwordx4 v[26:29], v132, s[40:41] offset:16
	global_load_dwordx4 v[30:33], v133, s[40:41] offset:16
	global_load_dwordx4 v[34:37], v130, s[40:41] offset:128
	global_load_dwordx4 v[38:41], v131, s[40:41] offset:128
	global_load_dwordx4 v[42:45], v132, s[40:41] offset:128
	global_load_dwordx4 v[46:49], v133, s[40:41] offset:128
	global_load_dwordx4 v[50:53], v130, s[40:41] offset:144
	global_load_dwordx4 v[54:57], v131, s[40:41] offset:144
	global_load_dwordx4 v[58:61], v132, s[40:41] offset:144
	global_load_dwordx4 v[62:65], v133, s[40:41] offset:144
	s_waitcnt vmcnt(15)
	v_pk_fma_f32 v[126:127], v[2:3], s[10:11], v[126:127] op_sel_hi:[1,0,1]
	v_pk_fma_f32 v[128:129], v[4:5], s[10:11], v[128:129] op_sel_hi:[1,0,1]
	global_store_dwordx4 v130, v[126:129], s[62:63]
	s_waitcnt vmcnt(15)
	v_pk_fma_f32 v[110:111], v[6:7], s[10:11], v[110:111] op_sel_hi:[1,0,1]
	v_pk_fma_f32 v[112:113], v[8:9], s[10:11], v[112:113] op_sel_hi:[1,0,1]
	global_store_dwordx4 v131, v[110:113], s[62:63]
	s_waitcnt vmcnt(15)
	v_pk_fma_f32 v[94:95], v[10:11], s[10:11], v[94:95] op_sel_hi:[1,0,1]
	v_pk_fma_f32 v[96:97], v[12:13], s[10:11], v[96:97] op_sel_hi:[1,0,1]
	global_store_dwordx4 v132, v[94:97], s[62:63]
	s_waitcnt vmcnt(15)
	v_pk_fma_f32 v[78:79], v[14:15], s[10:11], v[78:79] op_sel_hi:[1,0,1]
	v_pk_fma_f32 v[80:81], v[16:17], s[10:11], v[80:81] op_sel_hi:[1,0,1]
	global_store_dwordx4 v133, v[78:81], s[62:63]
	s_waitcnt vmcnt(15)
	v_pk_fma_f32 v[122:123], v[18:19], s[10:11], v[122:123] op_sel_hi:[1,0,1]
	v_pk_fma_f32 v[124:125], v[20:21], s[10:11], v[124:125] op_sel_hi:[1,0,1]
	global_store_dwordx4 v130, v[122:125], s[62:63] offset:16
	s_waitcnt vmcnt(15)
	v_pk_fma_f32 v[106:107], v[22:23], s[10:11], v[106:107] op_sel_hi:[1,0,1]
	v_pk_fma_f32 v[108:109], v[24:25], s[10:11], v[108:109] op_sel_hi:[1,0,1]
	global_store_dwordx4 v131, v[106:109], s[62:63] offset:16
	s_waitcnt vmcnt(15)
	v_pk_fma_f32 v[90:91], v[26:27], s[10:11], v[90:91] op_sel_hi:[1,0,1]
	v_pk_fma_f32 v[92:93], v[28:29], s[10:11], v[92:93] op_sel_hi:[1,0,1]
	global_store_dwordx4 v132, v[90:93], s[62:63] offset:16
	s_waitcnt vmcnt(15)
	v_pk_fma_f32 v[74:75], v[30:31], s[10:11], v[74:75] op_sel_hi:[1,0,1]
	v_pk_fma_f32 v[76:77], v[32:33], s[10:11], v[76:77] op_sel_hi:[1,0,1]
	global_store_dwordx4 v133, v[74:77], s[62:63] offset:16
	s_waitcnt vmcnt(15)
	v_pk_fma_f32 v[118:119], v[34:35], s[10:11], v[118:119] op_sel_hi:[1,0,1]
	v_pk_fma_f32 v[120:121], v[36:37], s[10:11], v[120:121] op_sel_hi:[1,0,1]
	global_store_dwordx4 v130, v[118:121], s[62:63] offset:128
	s_waitcnt vmcnt(15)
	v_pk_fma_f32 v[102:103], v[38:39], s[10:11], v[102:103] op_sel_hi:[1,0,1]
	v_pk_fma_f32 v[104:105], v[40:41], s[10:11], v[104:105] op_sel_hi:[1,0,1]
	global_store_dwordx4 v131, v[102:105], s[62:63] offset:128
	s_waitcnt vmcnt(15)
	v_pk_fma_f32 v[86:87], v[42:43], s[10:11], v[86:87] op_sel_hi:[1,0,1]
	v_pk_fma_f32 v[88:89], v[44:45], s[10:11], v[88:89] op_sel_hi:[1,0,1]
	global_store_dwordx4 v132, v[86:89], s[62:63] offset:128
	s_waitcnt vmcnt(15)
	v_pk_fma_f32 v[70:71], v[46:47], s[10:11], v[70:71] op_sel_hi:[1,0,1]
	v_pk_fma_f32 v[72:73], v[48:49], s[10:11], v[72:73] op_sel_hi:[1,0,1]
	global_store_dwordx4 v133, v[70:73], s[62:63] offset:128
	s_waitcnt vmcnt(15)
	v_pk_fma_f32 v[114:115], v[50:51], s[10:11], v[114:115] op_sel_hi:[1,0,1]
	v_pk_fma_f32 v[116:117], v[52:53], s[10:11], v[116:117] op_sel_hi:[1,0,1]
	global_store_dwordx4 v130, v[114:117], s[62:63] offset:144
	s_waitcnt vmcnt(15)
	v_pk_fma_f32 v[98:99], v[54:55], s[10:11], v[98:99] op_sel_hi:[1,0,1]
	v_pk_fma_f32 v[100:101], v[56:57], s[10:11], v[100:101] op_sel_hi:[1,0,1]
	global_store_dwordx4 v131, v[98:101], s[62:63] offset:144
	s_waitcnt vmcnt(15)
	v_pk_fma_f32 v[82:83], v[58:59], s[10:11], v[82:83] op_sel_hi:[1,0,1]
	v_pk_fma_f32 v[84:85], v[60:61], s[10:11], v[84:85] op_sel_hi:[1,0,1]
	global_store_dwordx4 v132, v[82:85], s[62:63] offset:144
	s_waitcnt vmcnt(15)
	v_pk_fma_f32 v[66:67], v[62:63], s[10:11], v[66:67] op_sel_hi:[1,0,1]
	v_pk_fma_f32 v[68:69], v[64:65], s[10:11], v[68:69] op_sel_hi:[1,0,1]
	global_store_dwordx4 v133, v[66:69], s[62:63] offset:144
	s_branch .Lepi_done_157

.LBB0_474:
	v_mov_b32_e32 v67, v169
	s_mov_b32 s11, s8
	v_lshrrev_b32_e32 v69, 4, v67
	v_ashrrev_i32_e32 v71, 3, v67
	v_lshrrev_b32_e32 v77, 1, v67
	v_and_b32_e32 v80, 4, v69
	v_and_b32_e32 v81, 3, v71
	v_and_b32_e32 v73, 7, v67
	v_xor_b32_e32 v75, v71, v67
	v_and_b32_e32 v77, 16, v77
	v_and_b32_e32 v79, 8, v69
	v_or_b32_e32 v82, v80, v81
	v_lshlrev_b32_e32 v75, 4, v75
	v_or3_b32 v77, v77, v79, v82
	v_bitop3_b32 v79, v80, v73, v81 bitop3:0x36
	v_lshlrev_b32_e32 v71, 7, v71
	v_lshlrev_b32_e32 v79, 4, v79
	v_and_or_b32 v115, v75, s24, v71
	v_lshl_or_b32 v114, v77, 7, v79
	v_lshlrev_b32_e32 v35, 7, v67
	v_bfe_u32 v34, v67, 4, 2
	v_and_b32_e32 v36, 0x780, v35
	v_and_b32_e32 v116, 0x2780, v35
	v_bitop3_b32 v35, v69, v73, 3 bitop3:0x6c
	v_mov_b32_e32 v75, v1
	v_lshlrev_b32_e32 v117, 4, v35
	v_lshlrev_b32_e32 v35, 6, v67
	v_bitop3_b32 v34, v34, v73, 4 bitop3:0x36
	v_mov_b32_e32 v73, v1
	v_mov_b32_e32 v67, v1
	v_mov_b32_e32 v69, v1
	v_mov_b32_e32 v77, v1
	v_mov_b32_e32 v71, v1
	v_mov_b32_e32 v79, v1
	v_lshl_add_u64 v[100:101], v[74:75], 1, s[0:1]
	s_mov_b32 s16, s10
	v_and_or_b32 v118, v35, s30, v36
	v_lshlrev_b32_e32 v119, 4, v34
	v_lshl_add_u64 v[98:99], v[72:73], 1, s[0:1]
	v_lshl_add_u64 v[102:103], v[76:77], 1, s[0:1]
	v_lshl_add_u64 v[104:105], v[78:79], 1, s[0:1]
	v_lshlrev_b64 v[106:107], 1, v[0:1]
	s_waitcnt lgkmcnt(8)
	v_lshlrev_b64 v[108:109], 1, v[66:67]
	v_lshlrev_b64 v[110:111], 1, v[68:69]
	v_lshlrev_b64 v[112:113], 1, v[70:71]
	s_mov_b32 s8, -2
	s_mov_b64 s[28:29], s[34:35]
	s_waitcnt vmcnt(0)
	s_waitcnt lgkmcnt(0)
	s_barrier
	v_lshrrev_b32_e32 v218, 6, v169
	v_lshlrev_b32_e32 v218, 10, v218
	v_lshrrev_b32_e32 v219, 3, v169
	v_readfirstlane_b32 s100, v218
	v_and_b32_e32 v218, 3, v219
	v_bfe_u32 v220, v219, 4, 1
	v_lshl_or_b32 v218, v220, 2, v218
	v_bfe_u32 v220, v219, 2, 1
	v_lshl_or_b32 v218, v220, 3, v218
	v_bfe_u32 v220, v219, 3, 1
	v_lshl_or_b32 v218, v220, 4, v218
	v_sub_u32_e32 v218, v218, v219
	v_mul_i32_i24_e32 v218, 0x800, v218
	v_and_b32_e32 v219, 7, v219
	v_lshlrev_b32_e32 v219, 4, v219
	v_add_u32_e32 v206, 0x4991000, v106
	v_xor_b32_e32 v164, v206, v219
	v_mov_b32_e32 v207, v98
	v_add_u32_e32 v165, v207, v218
	v_xor_b32_e32 v165, v165, v219
	v_add_u32_e32 v208, 0x4991000, v108
	v_xor_b32_e32 v166, v208, v219
	v_mov_b32_e32 v209, v100
	v_add_u32_e32 v167, v209, v218
	v_xor_b32_e32 v167, v167, v219
	v_add_u32_e32 v214, 0x4991000, v110
	v_xor_b32_e32 v198, v214, v219
	v_mov_b32_e32 v215, v102
	v_add_u32_e32 v199, v215, v218
	v_xor_b32_e32 v199, v199, v219
	v_add_u32_e32 v216, 0x4991000, v112
	v_xor_b32_e32 v200, v216, v219
	v_mov_b32_e32 v217, v104
	v_add_u32_e32 v201, v217, v218
	v_xor_b32_e32 v201, v201, v219
	s_setprio 1
	s_add_u32 s98, s28, 0x80
	s_addc_u32 s99, s29, 0
	v_add_u32_e32 v120, v117, v116
	v_add_u32_e32 v122, v117, v118
	v_add_u32_e32 v121, v119, v118
	ds_read_b128 v[124:127], v120 offset:16384
	ds_read_b128 v[128:131], v122
	ds_read_b128 v[144:147], v120 offset:18432
	ds_read_b128 v[156:159], v120 offset:20480
	ds_read_b128 v[160:163], v120 offset:22528
	ds_read_b128 v[132:135], v122 offset:2048
	ds_read_b128 v[148:151], v122 offset:4096
	ds_read_b128 v[152:155], v122 offset:6144
	s_add_u32 m0, s100, 0x8000
	s_waitcnt lgkmcnt(6)
	v_mfma_f32_16x16x32_bf16 v[34:37], v[124:127], v[128:131], 0
	global_load_lds_dwordx4 v164, s[98:99]
	s_waitcnt lgkmcnt(5)
	v_mfma_f32_16x16x32_bf16 v[94:97], v[144:147], v[128:131], 0
	ds_read_b128 v[194:197], v121
	s_add_u32 m0, s100, 0xc000
	s_waitcnt lgkmcnt(5)
	v_mfma_f32_16x16x32_bf16 v[38:41], v[156:159], v[128:131], 0
	global_load_lds_dwordx4 v165, s[98:99]
	s_waitcnt lgkmcnt(4)
	v_mfma_f32_16x16x32_bf16 v[90:93], v[160:163], v[128:131], 0
	v_add_u32_e32 v130, v119, v116
	ds_read_b128 v[202:205], v121 offset:2048
	s_add_u32 m0, s100, 0x9000
	s_waitcnt lgkmcnt(4)
	v_mfma_f32_16x16x32_bf16 v[42:45], v[124:127], v[132:135], 0
	global_load_lds_dwordx4 v166, s[98:99]
	v_mfma_f32_16x16x32_bf16 v[86:89], v[144:147], v[132:135], 0
	ds_read_b128 v[210:213], v121 offset:4096
	s_add_u32 m0, s100, 0xd000
	v_mfma_f32_16x16x32_bf16 v[46:49], v[156:159], v[132:135], 0
	global_load_lds_dwordx4 v167, s[98:99]
	v_mfma_f32_16x16x32_bf16 v[82:85], v[160:163], v[132:135], 0
	ds_read_b128 v[132:135], v121 offset:6144
	s_add_u32 m0, s100, 0xa000
	s_waitcnt lgkmcnt(5)
	v_mfma_f32_16x16x32_bf16 v[50:53], v[124:127], v[148:151], 0
	global_load_lds_dwordx4 v198, s[98:99]
	v_mfma_f32_16x16x32_bf16 v[78:81], v[144:147], v[148:151], 0
	ds_read_b128 v[222:225], v130 offset:16384
	s_add_u32 m0, s100, 0xe000
	v_mfma_f32_16x16x32_bf16 v[54:57], v[156:159], v[148:151], 0
	global_load_lds_dwordx4 v199, s[98:99]
	v_mfma_f32_16x16x32_bf16 v[70:73], v[160:163], v[148:151], 0
	ds_read_b128 v[148:151], v130 offset:18432
	s_add_u32 m0, s100, 0xb000
	s_waitcnt lgkmcnt(6)
	v_mfma_f32_16x16x32_bf16 v[58:61], v[124:127], v[152:155], 0
	global_load_lds_dwordx4 v200, s[98:99]
	v_mfma_f32_16x16x32_bf16 v[66:69], v[144:147], v[152:155], 0
	ds_read_b128 v[144:147], v130 offset:20480
	s_add_u32 m0, s100, 0xf000
	v_mfma_f32_16x16x32_bf16 v[62:65], v[156:159], v[152:155], 0
	global_load_lds_dwordx4 v201, s[98:99]
	v_mfma_f32_16x16x32_bf16 v[74:77], v[160:163], v[152:155], 0
	ds_read_b128 v[152:155], v130 offset:22528
	s_waitcnt lgkmcnt(3)
	v_mfma_f32_16x16x32_bf16 v[34:37], v[222:225], v[194:197], v[34:37]
	s_waitcnt lgkmcnt(2)
	v_mfma_f32_16x16x32_bf16 v[94:97], v[148:151], v[194:197], v[94:97]
	s_waitcnt lgkmcnt(1)
	v_mfma_f32_16x16x32_bf16 v[38:41], v[144:147], v[194:197], v[38:41]
	s_waitcnt lgkmcnt(0)
	v_mfma_f32_16x16x32_bf16 v[90:93], v[152:155], v[194:197], v[90:93]
	v_mfma_f32_16x16x32_bf16 v[42:45], v[222:225], v[202:205], v[42:45]
	v_mfma_f32_16x16x32_bf16 v[86:89], v[148:151], v[202:205], v[86:89]
	v_mfma_f32_16x16x32_bf16 v[46:49], v[144:147], v[202:205], v[46:49]
	v_mfma_f32_16x16x32_bf16 v[82:85], v[152:155], v[202:205], v[82:85]
	v_mfma_f32_16x16x32_bf16 v[50:53], v[222:225], v[210:213], v[50:53]
	v_mfma_f32_16x16x32_bf16 v[78:81], v[148:151], v[210:213], v[78:81]
	v_mfma_f32_16x16x32_bf16 v[54:57], v[144:147], v[210:213], v[54:57]
	v_mfma_f32_16x16x32_bf16 v[70:73], v[152:155], v[210:213], v[70:73]
	v_mfma_f32_16x16x32_bf16 v[58:61], v[222:225], v[132:135], v[58:61]
	v_mfma_f32_16x16x32_bf16 v[66:69], v[148:151], v[132:135], v[66:69]
	v_mfma_f32_16x16x32_bf16 v[62:65], v[144:147], v[132:135], v[62:65]
	v_mfma_f32_16x16x32_bf16 v[74:77], v[152:155], v[132:135], v[74:77]
	s_waitcnt vmcnt(0)
	s_setprio 0
	s_waitcnt lgkmcnt(0)
	s_barrier
	s_branch .Lk3_odd_475

.Lk3_odd_475:
	s_setprio 1
	s_add_u32 s98, s98, 0x80
	s_addc_u32 s99, s99, 0
	ds_read_b128 v[26:29], v120 offset:49152
	ds_read_b128 v[10:13], v122 offset:32768
	ds_read_b128 v[30:33], v120 offset:51200
	ds_read_b128 v[148:151], v120 offset:53248
	ds_read_b128 v[152:155], v120 offset:55296
	ds_read_b128 v[18:21], v122 offset:34816
	ds_read_b128 v[132:135], v122 offset:36864
	ds_read_b128 v[144:147], v122 offset:38912
	s_add_u32 m0, s100, 0x0
	s_waitcnt lgkmcnt(6)
	v_mfma_f32_16x16x32_bf16 v[34:37], v[26:29], v[10:13], v[34:37]
	global_load_lds_dwordx4 v164, s[98:99]
	s_waitcnt lgkmcnt(5)
	v_mfma_f32_16x16x32_bf16 v[94:97], v[30:33], v[10:13], v[94:97]
	ds_read_b128 v[160:163], v121 offset:32768
	s_add_u32 m0, s100, 0x4000
	s_waitcnt lgkmcnt(5)
	v_mfma_f32_16x16x32_bf16 v[38:41], v[148:151], v[10:13], v[38:41]
	global_load_lds_dwordx4 v165, s[98:99]
	s_waitcnt lgkmcnt(4)
	v_mfma_f32_16x16x32_bf16 v[90:93], v[152:155], v[10:13], v[90:93]
	ds_read_b128 v[194:197], v121 offset:34816
	s_add_u32 m0, s100, 0x1000
	s_waitcnt lgkmcnt(4)
	v_mfma_f32_16x16x32_bf16 v[42:45], v[26:29], v[18:21], v[42:45]
	global_load_lds_dwordx4 v166, s[98:99]
	v_mfma_f32_16x16x32_bf16 v[86:89], v[30:33], v[18:21], v[86:89]
	ds_read_b128 v[202:205], v121 offset:36864
	s_add_u32 m0, s100, 0x5000
	v_mfma_f32_16x16x32_bf16 v[46:49], v[148:151], v[18:21], v[46:49]
	global_load_lds_dwordx4 v167, s[98:99]
	v_mfma_f32_16x16x32_bf16 v[82:85], v[152:155], v[18:21], v[82:85]
	ds_read_b128 v[210:213], v121 offset:38912
	s_add_u32 m0, s100, 0x2000
	s_waitcnt lgkmcnt(5)
	v_mfma_f32_16x16x32_bf16 v[50:53], v[26:29], v[132:135], v[50:53]
	global_load_lds_dwordx4 v198, s[98:99]
	v_mfma_f32_16x16x32_bf16 v[78:81], v[30:33], v[132:135], v[78:81]
	ds_read_b128 v[222:225], v130 offset:49152
	s_add_u32 m0, s100, 0x6000
	v_mfma_f32_16x16x32_bf16 v[54:57], v[148:151], v[132:135], v[54:57]
	global_load_lds_dwordx4 v199, s[98:99]
	v_mfma_f32_16x16x32_bf16 v[70:73], v[152:155], v[132:135], v[70:73]
	ds_read_b128 v[132:135], v130 offset:51200
	s_add_u32 m0, s100, 0x3000
	s_waitcnt lgkmcnt(6)
	v_mfma_f32_16x16x32_bf16 v[58:61], v[26:29], v[144:147], v[58:61]
	global_load_lds_dwordx4 v200, s[98:99]
	v_mfma_f32_16x16x32_bf16 v[66:69], v[30:33], v[144:147], v[66:69]
	ds_read_b128 v[230:233], v130 offset:53248
	s_add_u32 m0, s100, 0x7000
	v_mfma_f32_16x16x32_bf16 v[62:65], v[148:151], v[144:147], v[62:65]
	global_load_lds_dwordx4 v201, s[98:99]
	v_mfma_f32_16x16x32_bf16 v[74:77], v[152:155], v[144:147], v[74:77]
	ds_read_b128 v[144:147], v130 offset:55296
	s_waitcnt lgkmcnt(3)
	v_mfma_f32_16x16x32_bf16 v[34:37], v[222:225], v[160:163], v[34:37]
	s_waitcnt lgkmcnt(2)
	v_mfma_f32_16x16x32_bf16 v[94:97], v[132:135], v[160:163], v[94:97]
	s_waitcnt lgkmcnt(1)
	v_mfma_f32_16x16x32_bf16 v[38:41], v[230:233], v[160:163], v[38:41]
	s_waitcnt lgkmcnt(0)
	v_mfma_f32_16x16x32_bf16 v[90:93], v[144:147], v[160:163], v[90:93]
	v_mfma_f32_16x16x32_bf16 v[42:45], v[222:225], v[194:197], v[42:45]
	v_mfma_f32_16x16x32_bf16 v[86:89], v[132:135], v[194:197], v[86:89]
	v_mfma_f32_16x16x32_bf16 v[46:49], v[230:233], v[194:197], v[46:49]
	v_mfma_f32_16x16x32_bf16 v[82:85], v[144:147], v[194:197], v[82:85]
	v_mfma_f32_16x16x32_bf16 v[50:53], v[222:225], v[202:205], v[50:53]
	v_mfma_f32_16x16x32_bf16 v[78:81], v[132:135], v[202:205], v[78:81]
	v_mfma_f32_16x16x32_bf16 v[54:57], v[230:233], v[202:205], v[54:57]
	v_mfma_f32_16x16x32_bf16 v[70:73], v[144:147], v[202:205], v[70:73]
	v_mfma_f32_16x16x32_bf16 v[58:61], v[222:225], v[210:213], v[58:61]
	v_mfma_f32_16x16x32_bf16 v[66:69], v[132:135], v[210:213], v[66:69]
	v_mfma_f32_16x16x32_bf16 v[62:65], v[230:233], v[210:213], v[62:65]
	v_mfma_f32_16x16x32_bf16 v[74:77], v[144:147], v[210:213], v[74:77]
	s_waitcnt vmcnt(0)
	s_setprio 0
	s_add_i32 s8, s8, 2
	s_add_u32 s28, s28, 0x100
	s_addc_u32 s29, s29, 0
	s_cmp_lt_u32 s8, 12
	s_waitcnt lgkmcnt(0)
	s_barrier
	s_cbranch_scc1 .LBB0_475
	v_mov_b32_e32 v2, v164
	v_mov_b32_e32 v3, v165
	v_mov_b32_e32 v4, v166
	v_mov_b32_e32 v5, v167
	v_mov_b32_e32 v6, v198
	v_mov_b32_e32 v7, v199
	v_mov_b32_e32 v8, v200
	v_mov_b32_e32 v9, v201
	s_add_u32 s98, s28, 0x80
	s_addc_u32 s99, s29, 0
	s_add_i32 s8, s11, s2
	s_cmpk_lt_u32 s8, 0x420
	s_cselect_b64 s[56:57], -1, 0
	s_and_b64 s[14:15], s[56:57], exec
	s_cselect_b32 s10, s8, s11
	s_mul_hi_u32 s11, s10, 0x3e0f83e1
	s_lshr_b32 s11, s11, 6
	s_mul_i32 s14, s11, 0x108
	v_mov_b32_e32 v0, v169
	s_sub_i32 s10, s10, s14
	s_lshl_b32 s11, s11, 3
	s_add_i32 s11, s11, s21
	s_and_b32 s14, s10, 7
	v_lshlrev_b32_e32 v98, 3, v0
	v_lshlrev_b32_e32 v0, 7, v0
	s_or_b32 s11, s11, s14
	v_and_b32_e32 v0, 0xfffffc00, v0
	v_lshl_add_u32 v0, s11, 17, v0
	v_and_or_b32 v0, v98, 56, v0
	v_mov_b32_e32 v98, v169
	s_lshl_b32 s10, s10, 4
	s_and_b32 s10, s10, 0x1f80
	v_lshrrev_b32_e32 v99, 3, v98
	v_lshlrev_b32_e32 v98, 3, v98
	v_add_u32_e32 v99, s10, v99
	v_and_b32_e32 v98, 56, v98
	v_add_u32_e32 v128, 0x8000, v0
	v_add_u32_e32 v136, 0x10000, v0
	v_lshl_or_b32 v160, v99, 10, v98
	v_add_u32_e32 v210, 0x18000, v0
	v_add_u32_e32 v198, 0x8000, v160
	v_add_u32_e32 v212, 0x10000, v160
	v_add_u32_e32 v214, 0x18000, v160
	s_setprio 1
	ds_read_b128 v[98:101], v120 offset:16384
	ds_read_b128 v[102:105], v122
	ds_read_b128 v[110:113], v120 offset:18432
	ds_read_b128 v[132:135], v120 offset:20480
	ds_read_b128 v[144:147], v120 offset:22528
	ds_read_b128 v[106:109], v122 offset:2048
	ds_read_b128 v[116:119], v122 offset:4096
	ds_read_b128 v[124:127], v122 offset:6144
	v_lshrrev_b32_e32 v14, 3, v169
	v_and_b32_e32 v15, 3, v14
	v_bfe_u32 v16, v14, 4, 1
	v_lshl_or_b32 v15, v16, 2, v15
	v_bfe_u32 v16, v14, 2, 1
	v_lshl_or_b32 v15, v16, 3, v15
	v_bfe_u32 v16, v14, 3, 1
	v_lshl_or_b32 v15, v16, 4, v15
	v_sub_u32_e32 v15, v15, v14
	v_mul_i32_i24_e32 v15, 0x400, v15
	v_and_b32_e32 v14, 7, v14
	v_lshlrev_b32_e32 v14, 3, v14
	v_xor_b32_e32 v0, v0, v14
	v_add_u32_e32 v160, v160, v15
	v_xor_b32_e32 v160, v160, v14
	v_xor_b32_e32 v128, v128, v14
	v_add_u32_e32 v198, v198, v15
	v_xor_b32_e32 v198, v198, v14
	v_xor_b32_e32 v136, v136, v14
	v_add_u32_e32 v212, v212, v15
	v_xor_b32_e32 v212, v212, v14
	v_xor_b32_e32 v210, v210, v14
	v_add_u32_e32 v214, v214, v15
	v_xor_b32_e32 v214, v214, v14
	v_mov_b32_e32 v161, v1
	v_mov_b32_e32 v129, v1
	v_mov_b32_e32 v199, v1
	v_mov_b32_e32 v137, v1
	v_mov_b32_e32 v213, v1
	v_mov_b32_e32 v211, v1
	v_mov_b32_e32 v215, v1
	v_lshl_add_u64 v[216:217], v[0:1], 1, s[48:49]
	v_lshl_add_u64 v[218:219], v[160:161], 1, s[50:51]
	v_lshl_add_u64 v[220:221], v[128:129], 1, s[48:49]
	v_lshl_add_u64 v[222:223], v[198:199], 1, s[50:51]
	v_lshl_add_u64 v[136:137], v[136:137], 1, s[48:49]
	v_lshl_add_u64 v[212:213], v[212:213], 1, s[50:51]
	v_lshl_add_u64 v[224:225], v[210:211], 1, s[48:49]
	v_lshl_add_u64 v[226:227], v[214:215], 1, s[50:51]
	s_add_u32 m0, s100, 0x8000
	s_waitcnt lgkmcnt(6)
	v_mfma_f32_16x16x32_bf16 v[148:151], v[98:101], v[102:105], v[34:37]
	global_load_lds_dwordx4 v2, s[98:99]
	s_waitcnt lgkmcnt(5)
	v_mfma_f32_16x16x32_bf16 v[94:97], v[110:113], v[102:105], v[94:97]
	ds_read_b128 v[152:155], v121
	s_add_u32 m0, s100, 0xc000
	s_waitcnt lgkmcnt(5)
	v_mfma_f32_16x16x32_bf16 v[156:159], v[132:135], v[102:105], v[38:41]
	global_load_lds_dwordx4 v3, s[98:99]
	s_waitcnt lgkmcnt(4)
	v_mfma_f32_16x16x32_bf16 v[90:93], v[144:147], v[102:105], v[90:93]
	ds_read_b128 v[102:105], v121 offset:2048
	s_add_u32 m0, s100, 0x9000
	s_waitcnt lgkmcnt(4)
	v_mfma_f32_16x16x32_bf16 v[160:163], v[98:101], v[106:109], v[42:45]
	global_load_lds_dwordx4 v4, s[98:99]
	v_mfma_f32_16x16x32_bf16 v[86:89], v[110:113], v[106:109], v[86:89]
	ds_read_b128 v[164:167], v121 offset:4096
	s_add_u32 m0, s100, 0xd000
	v_mfma_f32_16x16x32_bf16 v[194:197], v[132:135], v[106:109], v[46:49]
	global_load_lds_dwordx4 v5, s[98:99]
	v_mfma_f32_16x16x32_bf16 v[82:85], v[144:147], v[106:109], v[82:85]
	ds_read_b128 v[106:109], v121 offset:6144
	s_add_u32 m0, s100, 0xa000
	s_waitcnt lgkmcnt(5)
	v_mfma_f32_16x16x32_bf16 v[198:201], v[98:101], v[116:119], v[50:53]
	global_load_lds_dwordx4 v6, s[98:99]
	v_mfma_f32_16x16x32_bf16 v[78:81], v[110:113], v[116:119], v[78:81]
	ds_read_b128 v[202:205], v130 offset:16384
	s_add_u32 m0, s100, 0xe000
	v_mfma_f32_16x16x32_bf16 v[206:209], v[132:135], v[116:119], v[54:57]
	global_load_lds_dwordx4 v7, s[98:99]
	v_mfma_f32_16x16x32_bf16 v[70:73], v[144:147], v[116:119], v[70:73]
	ds_read_b128 v[116:119], v130 offset:18432
	s_add_u32 m0, s100, 0xb000
	s_waitcnt lgkmcnt(6)
	v_mfma_f32_16x16x32_bf16 v[98:101], v[98:101], v[124:127], v[58:61]
	global_load_lds_dwordx4 v8, s[98:99]
	v_mfma_f32_16x16x32_bf16 v[66:69], v[110:113], v[124:127], v[66:69]
	ds_read_b128 v[110:113], v130 offset:20480
	s_add_u32 m0, s100, 0xf000
	v_mfma_f32_16x16x32_bf16 v[132:135], v[132:135], v[124:127], v[62:65]
	global_load_lds_dwordx4 v9, s[98:99]
	v_mfma_f32_16x16x32_bf16 v[74:77], v[144:147], v[124:127], v[74:77]
	ds_read_b128 v[124:127], v130 offset:22528
	s_waitcnt lgkmcnt(3)
	v_mfma_f32_16x16x32_bf16 v[144:147], v[202:205], v[152:155], v[148:151]
	s_waitcnt lgkmcnt(2)
	v_mfma_f32_16x16x32_bf16 v[94:97], v[116:119], v[152:155], v[94:97]
	s_waitcnt lgkmcnt(1)
	v_mfma_f32_16x16x32_bf16 v[148:151], v[110:113], v[152:155], v[156:159]
	s_waitcnt lgkmcnt(0)
	v_mfma_f32_16x16x32_bf16 v[90:93], v[124:127], v[152:155], v[90:93]
	v_mfma_f32_16x16x32_bf16 v[152:155], v[202:205], v[102:105], v[160:163]
	v_mfma_f32_16x16x32_bf16 v[86:89], v[116:119], v[102:105], v[86:89]
	v_mfma_f32_16x16x32_bf16 v[156:159], v[110:113], v[102:105], v[194:197]
	v_mfma_f32_16x16x32_bf16 v[82:85], v[124:127], v[102:105], v[82:85]
	v_mfma_f32_16x16x32_bf16 v[102:105], v[202:205], v[164:167], v[198:201]
	v_mfma_f32_16x16x32_bf16 v[78:81], v[116:119], v[164:167], v[78:81]
	v_mfma_f32_16x16x32_bf16 v[160:163], v[110:113], v[164:167], v[206:209]
	v_mfma_f32_16x16x32_bf16 v[70:73], v[124:127], v[164:167], v[70:73]
	v_mfma_f32_16x16x32_bf16 v[98:101], v[202:205], v[106:109], v[98:101]
	v_mfma_f32_16x16x32_bf16 v[66:69], v[116:119], v[106:109], v[66:69]
	v_mfma_f32_16x16x32_bf16 v[110:113], v[110:113], v[106:109], v[132:135]
	v_mfma_f32_16x16x32_bf16 v[74:77], v[124:127], v[106:109], v[74:77]
	s_waitcnt vmcnt(0)
	s_setprio 0
	s_waitcnt lgkmcnt(0)
	s_barrier
	s_setprio 1
	ds_read_b128 v[26:29], v120 offset:49152
	ds_read_b128 v[10:13], v122 offset:32768
	ds_read_b128 v[18:21], v122 offset:34816
	ds_read_b128 v[30:33], v120 offset:51200
	ds_read_b128 v[106:109], v122 offset:36864
	ds_read_b128 v[114:117], v122 offset:38912
	ds_read_b128 v[122:125], v120 offset:53248
	ds_read_b128 v[126:129], v120 offset:55296
	s_add_u32 m0, s100, 0x0
	s_waitcnt lgkmcnt(6)
	v_mfma_f32_16x16x32_bf16 v[132:135], v[26:29], v[10:13], v[144:147]
	global_load_lds_dwordx4 v[216:217], off
	s_waitcnt lgkmcnt(4)
	v_mfma_f32_16x16x32_bf16 v[94:97], v[30:33], v[10:13], v[94:97]
	ds_read_b128 v[144:147], v121 offset:32768
	s_add_u32 m0, s100, 0x4000
	s_waitcnt lgkmcnt(2)
	v_mfma_f32_16x16x32_bf16 v[148:151], v[122:125], v[10:13], v[148:151]
	global_load_lds_dwordx4 v[218:219], off
	s_waitcnt lgkmcnt(1)
	v_mfma_f32_16x16x32_bf16 v[90:93], v[126:129], v[10:13], v[90:93]
	ds_read_b128 v[164:167], v121 offset:34816
	s_add_u32 m0, s100, 0x1000
	v_mfma_f32_16x16x32_bf16 v[152:155], v[26:29], v[18:21], v[152:155]
	global_load_lds_dwordx4 v[220:221], off
	v_mfma_f32_16x16x32_bf16 v[86:89], v[30:33], v[18:21], v[86:89]
	ds_read_b128 v[194:197], v121 offset:36864
	s_add_u32 m0, s100, 0x5000
	v_mfma_f32_16x16x32_bf16 v[156:159], v[122:125], v[18:21], v[156:159]
	global_load_lds_dwordx4 v[222:223], off
	v_mfma_f32_16x16x32_bf16 v[82:85], v[126:129], v[18:21], v[82:85]
	ds_read_b128 v[198:201], v121 offset:38912
	s_add_u32 m0, s100, 0x2000
	v_mfma_f32_16x16x32_bf16 v[202:205], v[26:29], v[106:109], v[102:105]
	global_load_lds_dwordx4 v[136:137], off
	v_mfma_f32_16x16x32_bf16 v[78:81], v[30:33], v[106:109], v[78:81]
	ds_read_b128 v[206:209], v130 offset:49152
	s_add_u32 m0, s100, 0x6000
	v_mfma_f32_16x16x32_bf16 v[160:163], v[122:125], v[106:109], v[160:163]
	global_load_lds_dwordx4 v[212:213], off
	v_mfma_f32_16x16x32_bf16 v[70:73], v[126:129], v[106:109], v[70:73]
	ds_read_b128 v[210:213], v130 offset:51200
	s_add_u32 m0, s100, 0x3000
	v_mfma_f32_16x16x32_bf16 v[214:217], v[26:29], v[114:117], v[98:101]
	global_load_lds_dwordx4 v[224:225], off
	v_mfma_f32_16x16x32_bf16 v[66:69], v[30:33], v[114:117], v[66:69]
	ds_read_b128 v[218:221], v130 offset:53248
	s_add_u32 m0, s100, 0x7000
	v_mfma_f32_16x16x32_bf16 v[222:225], v[122:125], v[114:117], v[110:113]
	global_load_lds_dwordx4 v[226:227], off
	v_mfma_f32_16x16x32_bf16 v[226:229], v[126:129], v[114:117], v[74:77]
	s_waitcnt lgkmcnt(2)
	v_mfma_f32_16x16x32_bf16 v[126:129], v[206:209], v[144:147], v[132:135]
	ds_read_b128 v[130:133], v130 offset:55296
	s_waitcnt lgkmcnt(2)
	v_mfma_f32_16x16x32_bf16 v[122:125], v[210:213], v[144:147], v[94:97]
	s_waitcnt lgkmcnt(1)
	v_mfma_f32_16x16x32_bf16 v[118:121], v[218:221], v[144:147], v[148:151]
	s_waitcnt lgkmcnt(0)
	v_mfma_f32_16x16x32_bf16 v[114:117], v[130:133], v[144:147], v[90:93]
	v_mfma_f32_16x16x32_bf16 v[110:113], v[206:209], v[164:167], v[152:155]
	v_mfma_f32_16x16x32_bf16 v[106:109], v[210:213], v[164:167], v[86:89]
	v_mfma_f32_16x16x32_bf16 v[102:105], v[218:221], v[164:167], v[156:159]
	v_mfma_f32_16x16x32_bf16 v[98:101], v[130:133], v[164:167], v[82:85]
	v_mfma_f32_16x16x32_bf16 v[94:97], v[206:209], v[194:197], v[202:205]
	v_mfma_f32_16x16x32_bf16 v[90:93], v[210:213], v[194:197], v[78:81]
	v_mfma_f32_16x16x32_bf16 v[86:89], v[218:221], v[194:197], v[160:163]
	v_mfma_f32_16x16x32_bf16 v[82:85], v[130:133], v[194:197], v[70:73]
	v_mfma_f32_16x16x32_bf16 v[74:77], v[206:209], v[198:201], v[214:217]
	v_mfma_f32_16x16x32_bf16 v[70:73], v[210:213], v[198:201], v[66:69]
	v_mfma_f32_16x16x32_bf16 v[66:69], v[218:221], v[198:201], v[222:225]
	v_mfma_f32_16x16x32_bf16 v[78:81], v[130:133], v[198:201], v[226:229]
	s_setprio 0
	s_cmpk_gt_u32 s16, 0x9ff
	s_cselect_b64 s[42:43], -1, 0
	s_and_b32 s17, s16, 0x1f00
	s_cmpk_eq_i32 s17, 0xe00
	s_cselect_b64 s[40:41], -1, 0
	s_cmpk_gt_u32 s16, 0x5ff
	s_cselect_b64 s[46:47], -1, 0
	s_cmpk_gt_u32 s16, 0xbff
	s_cselect_b64 s[62:63], -1, 0
	s_cmpk_lt_u32 s16, 0xd00
	s_cselect_b64 s[14:15], -1, 0
	s_and_b64 s[26:27], s[14:15], exec
	s_movk_i32 s21, 0xf300
	s_cselect_b32 s28, 0xfffff400, s21
	s_nor_b64 s[60:61], s[14:15], s[40:41]
	s_cmpk_gt_u32 s16, 0xfff
	s_cselect_b64 s[58:59], -1, 0
	s_cmpk_lt_u32 s16, 0xe00
	v_add_u32_e32 v0, s9, v141
	s_cselect_b64 s[14:15], -1, 0
	v_or_b32_e32 v136, v0, v140
	s_movk_i32 s21, 0xc0
	s_and_b64 s[14:15], s[14:15], exec
	v_mad_i64_i32 v[134:135], s[26:27], v136, s21, 0
	s_movk_i32 s21, 0x1fcf
	s_movk_i32 s14, 0xf100
	v_bitop3_b32 v144, v0, s21, v140 bitop3:0xc8
	v_ashrrev_i32_e32 v0, 5, v0
	s_cselect_b32 s15, 0xfffff300, s14
	s_mov_b32 s14, 0x18991000
	v_ashrrev_i32_e32 v137, 31, v136
	v_and_b32_e32 v0, 0xffffff00, v0
	s_cselect_b32 s14, s14, 0x19991000
	v_add_u32_e32 v145, s15, v0
	v_lshlrev_b64 v[132:133], 10, v[136:137]
	v_lshlrev_b64 v[130:131], 11, v[136:137]
	v_or_b32_e32 v0, s16, v142
	s_mov_b64 s[44:45], -1
	s_and_b64 vcc, exec, s[46:47]
	s_barrier
	s_cbranch_vccz .LBB0_496
	s_and_b64 vcc, exec, s[42:43]
	s_cbranch_vccz .LBB0_493
	s_and_b64 vcc, exec, s[62:63]
	s_cbranch_vccz .LBB0_490
	s_and_b64 vcc, exec, s[60:61]
	s_cbranch_vccz .LBB0_487
	s_and_b64 vcc, exec, s[58:59]
	s_cbranch_vccz .LBB0_484
	v_cmp_gt_u32_e32 vcc, s7, v0
	s_and_saveexec_b64 s[44:45], vcc
	s_cbranch_execz .LBB0_483
	v_mul_f32_e32 v137, 0xbfb8aa3b, v126
	v_exp_f32_e32 v137, v137
	v_mul_f32_e32 v143, 0xbfb8aa3b, v127
	v_exp_f32_e32 v143, v143
	v_mul_f32_e32 v147, 0xbfb8aa3b, v129
	v_add_f32_e32 v137, 1.0, v137
	v_rcp_f32_e32 v146, v137
	v_mul_f32_e32 v137, 0xbfb8aa3b, v128
	v_exp_f32_e32 v137, v137
	v_exp_f32_e32 v149, v147
	v_add_f32_e32 v143, 1.0, v143
	v_rcp_f32_e32 v147, v143
	v_add_f32_e32 v137, 1.0, v137
	v_mul_f32_e32 v143, 0xbfb8aa3b, v122
	v_rcp_f32_e32 v148, v137
	v_add_f32_e32 v137, 1.0, v149
	v_exp_f32_e32 v143, v143
	v_mul_f32_e32 v149, 0xbfb8aa3b, v123
	v_exp_f32_e32 v151, v149
	v_rcp_f32_e32 v149, v137
	v_add_f32_e32 v137, 1.0, v143
	v_mul_f32_e32 v143, 0xbfb8aa3b, v124
	v_rcp_f32_e32 v150, v137
	v_add_f32_e32 v137, 1.0, v151
	v_exp_f32_e32 v143, v143
	v_mul_f32_e32 v151, 0xbfb8aa3b, v125
	v_exp_f32_e32 v153, v151
	v_rcp_f32_e32 v151, v137
	v_add_f32_e32 v137, 1.0, v143
	v_rcp_f32_e32 v152, v137
	v_add_f32_e32 v137, 1.0, v153
	v_lshl_add_u64 v[154:155], s[34:35], 0, v[134:135]
	v_rcp_f32_e32 v153, v137
	v_lshl_add_u64 v[154:155], v[0:1], 2, v[154:155]
	v_add_co_u32_e32 v154, vcc, 0x438d000, v154
	s_nop 1
	v_addc_co_u32_e32 v155, vcc, 0, v155, vcc
	global_store_dwordx4 v[154:155], v[146:149], off
	global_store_dwordx4 v[154:155], v[150:153], off offset:16
